# ret_out: decay via scalar loads; q-rotary cos/sin loads hoisted into main load batch (spare VGPRs + v_mov), removing 3 exposed load round trips per task
# speedup vs baseline: 1.0072x; 1.0004x over previous
; __device__ __forceinline__ void ret_out(const bf16_t* proj, const float* cosT, const float* sinT, const float* decay, const float* gn_g, const float* gn_b,
;                         const bf16_t* states, bf16_t* mix, unsigned char* lds, int tid, int bx) {
;     ...
;     for (int task = bx; task < 1536; task += gridDim.x) {
;         int tl = tid; asm volatile("" : "+v"(tl));
;         const int lane = tl & 63, fr = lane & 15, fq = lane >> 4, c = tl >> 2, part = tl & 3, cw = c ^ (part << 4);
;         const int n = task & 31, bh = task >> 5, b = bh / 6, h = bh % 6;
;         const float lgf2 = -__expf(decay[h]) * 1.4426950408889634f, lgb2 = -__expf(decay[6 + h]) * 1.4426950408889634f;
;         const int cq = 16 * wave + fr, tq = n * 128 + cq; const size_t rowq = (size_t)(b * SEQ + tq) * LDR;
;         __syncthreads();
;         {
;             const char* spb = (const char*)(states + ((size_t)(bh * 2) * 32 + n) * 16384);
; #pragma unroll
;             for (int dir = 0; dir < 2; ++dir)
; #pragma unroll
;                 for (int q4 = 0; q4 < 4; ++q4) { const int pc = wave + 8 * q4, e = 4 * pc + (lane >> 4), ch = (lane & 15) ^ (e & 15);
;                     __builtin_amdgcn_global_load_lds((const unsigned*)(spb + (size_t)dir * (32 * 16384 * 2) + e * 256 + ch * 16), (LAS unsigned*)(ldsl + ST_OFF + dir * 32768 + pc * 1024), 16, 0, 0); }
;         }
;         u32x4 qr[4]; float4 qc[2][2], qs[2][2];
;         { const bf16_t* qp = proj + rowq + h * 128 + 8 * fq;
; #pragma unroll
;           for (int ks = 0; ks < 4; ++ks) qr[ks] = *(const u32x4*)(qp + 32 * ks);
; #pragma unroll
;           for (int k2 = 0; k2 < 2; ++k2) { const float* cp = cosT + tq * 64 + 32 * k2 + 8 * fq; const float* snp = sinT + tq * 64 + 32 * k2 + 8 * fq;
;               qc[k2][0] = *(const float4*)cp; qc[k2][1] = *(const float4*)(cp + 4); qs[k2][0] = *(const float4*)snp; qs[k2][1] = *(const float4*)(snp + 4); } }
;         {
;             const int t = n * 128 + c; const size_t row = (size_t)(b * SEQ + t) * LDR;
;             const bf16_t* kp = proj + row + 768 + h * 128 + 16 * part;
;             const u32x4 k1a = *(const u32x4*)kp, k1b = *(const u32x4*)(kp + 8), k2a = *(const u32x4*)(kp + 64), k2b = *(const u32x4*)(kp + 72);
;             const float* cp = cosT + t * 64 + 16 * part; const float* snp = sinT + t * 64 + 16 * part;
;             const int cpv = tl >> 3, p8v = tl & 7, c0v = 2 * cpv;
.LBB0_189:
	s_ashr_i32 s15, s49, 5
	s_mul_hi_i32 s0, s15, 0x2aaaaaab
	s_lshr_b32 s1, s0, 31
	s_add_i32 s17, s0, s1
	s_mul_i32 s0, s17, 6
	s_sub_i32 s36, s15, s0
	s_ashr_i32 s37, s36, 31
	s_and_b32 s14, s49, 31
	s_lshl_b64 s[0:1], s[36:37], 2
	s_add_u32 s0, s6, s0
	v_mov_b32_e32 v22, v60
	s_addc_u32 s1, s19, s1
	s_load_dword s100, s[0:1], 0x0
	s_load_dword s101, s[0:1], 0x18
	s_lshl_b32 s18, s14, 7
	s_lshl_b32 s37, s17, 12
	v_bfe_u32 v84, v22, 4, 2
	v_bitop3_b32 v4, v84, v22, s29 bitop3:0x36
	v_lshlrev_b32_e32 v4, 4, v4
	v_and_b32_e32 v154, 0xf0, v4
	v_bitop3_b32 v4, v84, v22, s31 bitop3:0x36
	v_lshlrev_b32_e32 v4, 4, v4
	v_and_b32_e32 v4, 0xf0, v4
	v_mov_b32_e32 v5, v155
	v_bitop3_b32 v10, v84, v22, s35 bitop3:0x36
	v_lshlrev_b32_e32 v10, 4, v10
	v_and_b32_e32 v10, 0xf0, v10
	v_mov_b32_e32 v11, v155
	v_bitop3_b32 v14, v84, v22, s45 bitop3:0x36
	v_lshlrev_b32_e32 v14, 4, v14
	v_and_b32_e32 v14, 0xf0, v14
	v_mov_b32_e32 v15, v155
	v_and_b32_e32 v83, 15, v22
	v_or_b32_e32 v86, s28, v83
	v_add_u32_e32 v18, s18, v86
	v_add_u32_e32 v80, s37, v18
	v_mov_b64_e32 v[40:41], s[22:23]
	v_lshlrev_b32_e32 v18, 6, v18
	v_lshlrev_b32_e32 v62, 4, v84
	v_mov_b32_e32 v63, v155
	v_ashrrev_i32_e32 v19, 31, v18
	v_lshlrev_b64 v[20:21], 2, v[18:19]
	v_lshl_add_u64 v[18:19], s[38:39], 0, v[20:21]
	v_lshlrev_b32_e32 v24, 5, v84
	v_mov_b32_e32 v25, v155
	v_lshl_add_u64 v[20:21], s[40:41], 0, v[20:21]
	v_lshl_add_u64 v[18:19], v[18:19], 0, v[24:25]
	v_lshl_add_u64 v[20:21], v[20:21], 0, v[24:25]
	v_lshlrev_b32_e32 v26, 4, v22
	v_and_b32_e32 v108, 48, v26
	v_lshlrev_b32_e32 v46, 2, v108
	v_mov_b32_e32 v47, v155
	v_lshlrev_b32_e32 v100, 1, v108
	v_mov_b32_e32 v101, v155
	v_lshrrev_b32_e32 v85, 4, v22
	v_ashrrev_i32_e32 v81, 31, v80
	s_waitcnt lgkmcnt(0)
	v_mov_b32_e32 v0, s100
	v_mul_f32_e32 v0, 0x3fb8aa3b, v0
	v_exp_f32_e32 v16, v0
	s_lshl_b32 s0, s15, 1
	s_ashr_i32 s1, s0, 31
	s_lshl_b64 s[0:1], s[0:1], 20
	s_add_u32 s0, s24, s0
	s_addc_u32 s1, s25, s1
	s_lshl_b32 s14, s14, 15
	s_add_u32 s14, s0, s14
	s_addc_u32 s15, s1, 0
	s_add_i32 m0, s55, s30
	s_barrier
	v_mul_f32_e32 v87, 0xbfb8aa3b, v16
	v_mov_b32_e32 v0, s101
	v_mul_f32_e32 v0, 0x3fb8aa3b, v0
	v_exp_f32_e32 v23, v0
	v_or_b32_e32 v0, s29, v84
	v_lshlrev_b32_e32 v0, 8, v0
	v_ashrrev_i32_e32 v1, 31, v0
	v_lshl_add_u64 v[2:3], s[14:15], 0, v[0:1]
	v_lshl_add_u64 v[2:3], v[2:3], 0, v[154:155]
	global_load_lds_dwordx4 v[2:3], off
	v_or_b32_e32 v2, s31, v84
	v_lshlrev_b32_e32 v2, 8, v2
	v_ashrrev_i32_e32 v3, 31, v2
	v_lshl_add_u64 v[6:7], s[14:15], 0, v[2:3]
	v_lshl_add_u64 v[6:7], v[6:7], 0, v[4:5]
	s_add_i32 m0, s55, s34
	s_nop 0
	global_load_lds_dwordx4 v[6:7], off
	v_or_b32_e32 v6, s35, v84
	v_lshlrev_b32_e32 v6, 8, v6
	v_ashrrev_i32_e32 v7, 31, v6
	v_lshl_add_u64 v[8:9], s[14:15], 0, v[6:7]
	v_lshl_add_u64 v[8:9], v[8:9], 0, v[10:11]
	s_add_i32 m0, s55, s44
	s_nop 0
	global_load_lds_dwordx4 v[8:9], off
	v_or_b32_e32 v8, s45, v84
	v_lshlrev_b32_e32 v8, 8, v8
	s_add_i32 m0, s55, s48
	v_ashrrev_i32_e32 v9, 31, v8
	s_add_u32 s0, s14, 0x100000
	v_lshl_add_u64 v[12:13], s[14:15], 0, v[8:9]
	s_addc_u32 s1, s15, 0
	v_lshl_add_u64 v[12:13], v[12:13], 0, v[14:15]
	v_lshl_add_u64 v[0:1], s[0:1], 0, v[0:1]
	global_load_lds_dwordx4 v[12:13], off
	v_lshl_add_u64 v[0:1], v[0:1], 0, v[154:155]
	s_add_i32 m0, s50, s30
	v_lshlrev_b32_e32 v154, 3, v84
	global_load_lds_dwordx4 v[0:1], off
	v_lshl_add_u64 v[0:1], s[0:1], 0, v[2:3]
	v_lshl_add_u64 v[0:1], v[0:1], 0, v[4:5]
	s_add_i32 m0, s50, s34
	s_add_i32 s49, s49, s3
	global_load_lds_dwordx4 v[0:1], off
	v_lshl_add_u64 v[0:1], s[0:1], 0, v[6:7]
	v_lshl_add_u64 v[0:1], v[0:1], 0, v[10:11]
	s_add_i32 m0, s50, s44
	s_nop 0
	global_load_lds_dwordx4 v[0:1], off
	v_lshl_add_u64 v[0:1], s[0:1], 0, v[8:9]
	v_lshl_add_u64 v[0:1], v[0:1], 0, v[14:15]
	s_add_i32 m0, s50, s48
	s_nop 0
	global_load_lds_dwordx4 v[0:1], off
	v_mad_i64_i32 v[0:1], s[0:1], v80, s59, v[40:41]
	s_lshl_b32 s0, s36, 7
	s_ashr_i32 s1, s0, 31
	s_lshl_b64 s[46:47], s[0:1], 1
	v_lshl_add_u64 v[16:17], v[0:1], 0, s[46:47]
	v_lshl_add_u64 v[12:13], v[16:17], 0, v[62:63]
	v_ashrrev_i32_e32 v63, 2, v22
	v_add_u32_e32 v42, s18, v63
	v_add_u32_e32 v24, s37, v42
	v_lshlrev_b32_e32 v42, 6, v42
	v_ashrrev_i32_e32 v43, 31, v42
	v_lshlrev_b64 v[42:43], 2, v[42:43]
	v_mad_i64_i32 v[24:25], s[0:1], v24, s59, v[40:41]
	v_lshl_add_u64 v[44:45], s[38:39], 0, v[42:43]
	v_lshl_add_u64 v[42:43], s[40:41], 0, v[42:43]
	v_lshl_add_u64 v[96:97], v[42:43], 0, v[46:47]
	v_and_b32_e32 v42, -2, v63
	s_or_b32 s0, s37, s18
	v_lshl_add_u64 v[24:25], v[24:25], 0, s[46:47]
	v_add_u32_e32 v42, s0, v42
	v_lshl_add_u64 v[36:37], v[24:25], 0, v[100:101]
	v_and_b32_e32 v101, 7, v22
	v_mad_i64_i32 v[40:41], s[0:1], v42, s59, v[40:41]
	v_lshl_add_u64 v[40:41], v[40:41], 0, s[46:47]
	v_lshlrev_b32_e32 v42, 5, v101
	v_mov_b32_e32 v43, v155
	v_lshl_add_u64 v[48:49], v[40:41], 0, v[42:43]
	s_mov_b64 s[0:1], 0x2600
	global_load_dwordx4 v[0:3], v[12:13], off
	global_load_dwordx4 v[8:11], v[12:13], off offset:64
	global_load_dwordx4 v[4:7], v[12:13], off offset:128
	s_nop 0
	global_load_dwordx4 v[12:15], v[12:13], off offset:192
	s_nop 0
	global_load_dwordx4 v[24:27], v[36:37], off offset:1552
	global_load_dwordx4 v[28:31], v[36:37], off offset:1536
	global_load_dwordx4 v[32:35], v[36:37], off offset:1680
	s_nop 0
	global_load_dwordx4 v[36:39], v[36:37], off offset:1664
	v_lshl_add_u64 v[72:73], v[44:45], 0, v[46:47]
	global_load_dwordx4 v[40:43], v[48:49], off offset:3088
	global_load_dwordx4 v[44:47], v[48:49], off offset:3072
	v_lshl_add_u64 v[52:53], v[48:49], 0, s[0:1]
	v_add_co_u32_e32 v48, vcc, s98, v48
	s_mov_b64 s[0:1], 0x1200
	s_nop 0
	v_addc_co_u32_e32 v49, vcc, 0, v49, vcc
	global_load_dwordx4 v[48:51], v[48:49], off offset:1536
	s_nop 0
	global_load_dwordx4 v[52:55], v[52:53], off offset:16
	s_nop 0
	global_load_dwordx4 v[56:59], v[72:73], off offset:48
	global_load_dwordx4 v[64:67], v[72:73], off offset:32
	global_load_dwordx4 v[68:71], v[72:73], off offset:16
	s_nop 0
	global_load_dwordx4 v[72:75], v[72:73], off
	s_nop 0
	global_load_dwordx4 v[76:79], v[96:97], off offset:48
	global_load_dwordx4 v[88:91], v[96:97], off offset:32
	global_load_dwordx4 v[92:95], v[96:97], off offset:16
	s_nop 0
	global_load_dwordx4 v[96:99], v[96:97], off
	global_load_dwordx4 v[184:187], v[18:19], off offset:16
	global_load_dwordx4 v[188:191], v[18:19], off
	global_load_dwordx4 v[192:195], v[20:21], off offset:16
	global_load_dwordx4 v[196:199], v[20:21], off
	global_load_dwordx4 v[200:203], v[18:19], off offset:144
	global_load_dwordx4 v[204:207], v[18:19], off offset:128
	global_load_dwordx4 v[208:211], v[20:21], off offset:144
	global_load_dwordx4 v[212:215], v[20:21], off offset:128
	s_waitcnt vmcnt(0)
; __device__ __forceinline__ float bf_lo(unsigned u) { return __uint_as_float(u << 16); }
; __device__ __forceinline__ float bf_hi(unsigned u) { return __uint_as_float(u & 0xffff0000u); }
; __device__ __forceinline__ void ret_out(const bf16_t* proj, const float* cosT, const float* sinT, const float* decay, const float* gn_g, const float* gn_b,
;                         const bf16_t* states, bf16_t* mix, unsigned char* lds, int tid, int bx) {
;     ...
;           for (int k2 = 0; k2 < 2; ++k2) { const float* cp = cosT + tq * 64 + 32 * k2 + 8 * fq; const float* snp = sinT + tq * 64 + 32 * k2 + 8 * fq;
;               qc[k2][0] = *(const float4*)cp; qc[k2][1] = *(const float4*)(cp + 4); qs[k2][0] = *(const float4*)snp; qs[k2][1] = *(const float4*)(snp + 4); } }
;     ...
;             const unsigned k1w[8] = {k1a.x, k1a.y, k1a.z, k1a.w, k1b.x, k1b.y, k1b.z, k1b.w}, k2w[8] = {k2a.x, k2a.y, k2a.z, k2a.w, k2b.x, k2b.y, k2b.z, k2b.w};
;             unsigned r1[8], r2[8];
; #pragma unroll
;             for (int w2 = 0; w2 < 8; ++w2) {
;                 const float a1 = bf_lo(k1w[w2]), b1 = bf_hi(k1w[w2]), a2 = bf_lo(k2w[w2]), b2 = bf_hi(k2w[w2]);
;                 r1[w2] = cvt_pk_bf16(a1 * cs[2 * w2] - a2 * sn[2 * w2], b1 * cs[2 * w2 + 1] - b2 * sn[2 * w2 + 1]);
;                 r2[w2] = cvt_pk_bf16(a1 * sn[2 * w2] + a2 * cs[2 * w2], b1 * sn[2 * w2 + 1] + b2 * cs[2 * w2 + 1]);
;             }
;             *(u32x4*)(Kl + c * LP + 16 * part) = (u32x4){r1[0], r1[1], r1[2], r1[3]}; *(u32x4*)(Kl + c * LP + 16 * part + 8) = (u32x4){r1[4], r1[5], r1[6], r1[7]};
;             *(u32x4*)(Kl + c * LP + 64 + 16 * part) = (u32x4){r2[0], r2[1], r2[2], r2[3]}; *(u32x4*)(Kl + c * LP + 64 + 16 * part + 8) = (u32x4){r2[4], r2[5], r2[6], r2[7]};
;             { const unsigned t0w[8] = {vv[0].x, vv[0].y, vv[0].z, vv[0].w, vv[1].x, vv[1].y, vv[1].z, vv[1].w}, t1w[8] = {vv[2].x, vv[2].y, vv[2].z, vv[2].w, vv[3].x, vv[3].y, vv[3].z, vv[3].w};
;               unsigned* V32 = (unsigned*)(Vl + (16 * p8v) * LP + (c0v ^ ((p8v & 3) << 4)));
; #pragma unroll
;               for (int j = 0; j < 16; ++j) { const unsigned x0 = (j & 1) ? (t0w[j >> 1] >> 16) : (t0w[j >> 1] & 0xffffu), x1 = (j & 1) ? (t1w[j >> 1] & 0xffff0000u) : (t1w[j >> 1] << 16);
;                   V32[j * (LP / 2)] = x0 | x1; } }
	v_lshlrev_b32_e32 v102, 16, v28
	v_and_b32_e32 v103, 0xffff0000, v28
	v_lshlrev_b32_e32 v104, 16, v36
	v_and_b32_e32 v105, 0xffff0000, v36
	v_pk_mul_f32 v[106:107], v[96:97], v[104:105]
	v_pk_mul_f32 v[96:97], v[96:97], v[102:103]
	v_pk_fma_f32 v[106:107], v[72:73], v[102:103], v[106:107] neg_lo:[0,0,1] neg_hi:[0,0,1]
	v_pk_fma_f32 v[72:73], v[72:73], v[104:105], v[96:97]
	v_lshlrev_b32_e32 v96, 16, v37
	v_and_b32_e32 v97, 0xffff0000, v37
	v_cvt_pk_bf16_f32 v36, v72, v73
	v_lshlrev_b32_e32 v72, 16, v29
	v_and_b32_e32 v73, 0xffff0000, v29
	v_pk_mul_f32 v[102:103], v[98:99], v[96:97]
	v_cvt_pk_bf16_f32 v28, v106, v107
	v_pk_fma_f32 v[102:103], v[74:75], v[72:73], v[102:103] neg_lo:[0,0,1] neg_hi:[0,0,1]
	v_pk_mul_f32 v[72:73], v[98:99], v[72:73]
	v_cvt_pk_bf16_f32 v29, v102, v103
	v_pk_fma_f32 v[72:73], v[74:75], v[96:97], v[72:73]
	v_lshlrev_b32_e32 v74, 16, v38
	v_and_b32_e32 v75, 0xffff0000, v38
	v_cvt_pk_bf16_f32 v37, v72, v73
	v_lshlrev_b32_e32 v72, 16, v30
	v_and_b32_e32 v73, 0xffff0000, v30
	v_pk_mul_f32 v[96:97], v[92:93], v[74:75]
	s_nop 0
	v_pk_fma_f32 v[96:97], v[68:69], v[72:73], v[96:97] neg_lo:[0,0,1] neg_hi:[0,0,1]
	v_pk_mul_f32 v[72:73], v[92:93], v[72:73]
	v_cvt_pk_bf16_f32 v30, v96, v97
	v_pk_fma_f32 v[68:69], v[68:69], v[74:75], v[72:73]
	v_lshlrev_b32_e32 v72, 16, v39
	v_and_b32_e32 v73, 0xffff0000, v39
	v_cvt_pk_bf16_f32 v38, v68, v69
	v_lshlrev_b32_e32 v68, 16, v31
	v_and_b32_e32 v69, 0xffff0000, v31
	v_pk_mul_f32 v[74:75], v[94:95], v[72:73]
	s_nop 0
	v_pk_fma_f32 v[74:75], v[70:71], v[68:69], v[74:75] neg_lo:[0,0,1] neg_hi:[0,0,1]
	v_pk_mul_f32 v[68:69], v[94:95], v[68:69]
	v_cvt_pk_bf16_f32 v31, v74, v75
	v_pk_fma_f32 v[68:69], v[70:71], v[72:73], v[68:69]
	v_lshlrev_b32_e32 v70, 16, v32
	v_and_b32_e32 v71, 0xffff0000, v32
	v_cvt_pk_bf16_f32 v39, v68, v69
	v_lshlrev_b32_e32 v68, 16, v24
	v_and_b32_e32 v69, 0xffff0000, v24
	v_pk_mul_f32 v[72:73], v[88:89], v[70:71]
	s_nop 0
	v_pk_fma_f32 v[72:73], v[64:65], v[68:69], v[72:73] neg_lo:[0,0,1] neg_hi:[0,0,1]
	v_pk_mul_f32 v[68:69], v[88:89], v[68:69]
	v_cvt_pk_bf16_f32 v24, v72, v73
	v_pk_fma_f32 v[64:65], v[64:65], v[70:71], v[68:69]
	v_lshlrev_b32_e32 v68, 16, v33
	v_and_b32_e32 v69, 0xffff0000, v33
	v_cvt_pk_bf16_f32 v32, v64, v65
	v_lshlrev_b32_e32 v64, 16, v25
	v_and_b32_e32 v65, 0xffff0000, v25
	v_pk_mul_f32 v[70:71], v[90:91], v[68:69]
	s_nop 0
	v_pk_fma_f32 v[70:71], v[66:67], v[64:65], v[70:71] neg_lo:[0,0,1] neg_hi:[0,0,1]
	v_pk_mul_f32 v[64:65], v[90:91], v[64:65]
	v_cvt_pk_bf16_f32 v25, v70, v71
	v_pk_fma_f32 v[64:65], v[66:67], v[68:69], v[64:65]
	v_lshlrev_b32_e32 v66, 16, v34
	v_and_b32_e32 v67, 0xffff0000, v34
	v_cvt_pk_bf16_f32 v33, v64, v65
	v_lshlrev_b32_e32 v64, 16, v26
	v_and_b32_e32 v65, 0xffff0000, v26
	v_pk_mul_f32 v[68:69], v[76:77], v[66:67]
	s_nop 0
	v_pk_fma_f32 v[68:69], v[56:57], v[64:65], v[68:69] neg_lo:[0,0,1] neg_hi:[0,0,1]
	v_pk_mul_f32 v[64:65], v[76:77], v[64:65]
	v_cvt_pk_bf16_f32 v26, v68, v69
	v_pk_fma_f32 v[56:57], v[56:57], v[66:67], v[64:65]
	v_lshlrev_b32_e32 v64, 16, v35
	v_and_b32_e32 v65, 0xffff0000, v35
	v_cvt_pk_bf16_f32 v34, v56, v57
	v_lshlrev_b32_e32 v56, 16, v27
	v_and_b32_e32 v57, 0xffff0000, v27
	v_pk_mul_f32 v[66:67], v[78:79], v[64:65]
	s_nop 0
	v_pk_fma_f32 v[66:67], v[58:59], v[56:57], v[66:67] neg_lo:[0,0,1] neg_hi:[0,0,1]
	v_pk_mul_f32 v[56:57], v[78:79], v[56:57]
	v_cvt_pk_bf16_f32 v27, v66, v67
	v_pk_fma_f32 v[56:57], v[58:59], v[64:65], v[56:57]
	s_nop 0
	v_cvt_pk_bf16_f32 v35, v56, v57
	v_mul_lo_u32 v56, v63, s52
	v_add3_u32 v56, 0, v56, v100
	ds_write_b128 v56, v[28:31]
	ds_write_b128 v56, v[24:27] offset:16
	ds_write_b128 v56, v[36:39] offset:128
	ds_write_b128 v56, v[32:35] offset:144
	v_bitop3_b32 v25, v63, v108, -2 bitop3:0x6c
	v_mul_u32_u24_e32 v24, 0x1100, v101
	v_lshlrev_b32_e32 v25, 1, v25
	v_add3_u32 v24, 0, v24, v25
	v_and_b32_e32 v25, 0xffff, v44
	v_lshrrev_b32_e32 v26, 16, v44
	v_lshl_or_b32 v25, v48, 16, v25
	v_and_or_b32 v26, v48, s51, v26
	v_add_u32_e32 v27, 0x8800, v24
	ds_write2_b32 v27, v25, v26 offset1:68
	v_and_b32_e32 v25, 0xffff, v45
	v_lshrrev_b32_e32 v26, 16, v45
	v_lshl_or_b32 v25, v49, 16, v25
	v_and_or_b32 v26, v49, s51, v26
	ds_write2_b32 v27, v25, v26 offset0:136 offset1:204
	v_and_b32_e32 v25, 0xffff, v46
	v_lshrrev_b32_e32 v26, 16, v46
	v_lshl_or_b32 v25, v50, 16, v25
	v_and_or_b32 v26, v50, s51, v26
	v_add_u32_e32 v27, 0x8c00, v24
	ds_write2_b32 v27, v25, v26 offset0:16 offset1:84
	v_and_b32_e32 v25, 0xffff, v47
	v_lshrrev_b32_e32 v26, 16, v47
	v_lshl_or_b32 v25, v51, 16, v25
	v_and_or_b32 v26, v51, s51, v26
	ds_write2_b32 v27, v25, v26 offset0:152 offset1:220
	v_and_b32_e32 v25, 0xffff, v40
	v_lshrrev_b32_e32 v26, 16, v40
	v_lshl_or_b32 v25, v52, 16, v25
	v_and_or_b32 v26, v52, s51, v26
	v_add_u32_e32 v27, 0x9000, v24
	ds_write2_b32 v27, v25, v26 offset0:32 offset1:100
	v_and_b32_e32 v25, 0xffff, v41
	v_lshrrev_b32_e32 v26, 16, v41
	v_lshl_or_b32 v25, v53, 16, v25
	v_and_or_b32 v26, v53, s51, v26
	ds_write2_b32 v27, v25, v26 offset0:168 offset1:236
	v_and_b32_e32 v25, 0xffff, v42
	v_lshrrev_b32_e32 v26, 16, v42
	v_lshl_or_b32 v25, v54, 16, v25
	v_and_or_b32 v26, v54, s51, v26
	v_add_u32_e32 v24, 0x9400, v24
	ds_write2_b32 v24, v25, v26 offset0:48 offset1:116
	v_and_b32_e32 v25, 0xffff, v43
	v_lshrrev_b32_e32 v26, 16, v43
	v_lshl_or_b32 v25, v55, 16, v25
	v_and_or_b32 v26, v55, s51, v26
	ds_write2_b32 v24, v25, v26 offset0:184 offset1:252
	v_mov_b32_e32 v24, v184
	v_mov_b32_e32 v25, v185
	v_mov_b32_e32 v26, v186
	v_mov_b32_e32 v27, v187
	v_mov_b32_e32 v28, v188
	v_mov_b32_e32 v29, v189
	v_mov_b32_e32 v30, v190
	v_mov_b32_e32 v31, v191
	v_mov_b32_e32 v32, v192
; __device__ __forceinline__ float bf_lo(unsigned u) { return __uint_as_float(u << 16); }
; __device__ __forceinline__ float bf_hi(unsigned u) { return __uint_as_float(u & 0xffff0000u); }
; __device__ __forceinline__ void ret_out(const bf16_t* proj, const float* cosT, const float* sinT, const float* decay, const float* gn_g, const float* gn_b,
;                         const bf16_t* states, bf16_t* mix, unsigned char* lds, int tid, int bx) {
;     ...
;         asm volatile("s_waitcnt vmcnt(0)" ::: "memory");
;         __syncthreads();
;         u32x2 gwv[8];
;         { const bf16_t* gp0 = proj + rowq + 2304 + h * 128 + 4 * fq;
; #pragma unroll
;           for (int e8 = 0; e8 < 8; ++e8) gwv[e8] = *(const u32x2*)(gp0 + 16 * e8); }
;         bf16x8 qf[4];
; #pragma unroll
;         for (int k2 = 0; k2 < 2; ++k2) {
;             const float cs[8] = {qc[k2][0].x, qc[k2][0].y, qc[k2][0].z, qc[k2][0].w, qc[k2][1].x, qc[k2][1].y, qc[k2][1].z, qc[k2][1].w};
;             const float sn[8] = {qs[k2][0].x, qs[k2][0].y, qs[k2][0].z, qs[k2][0].w, qs[k2][1].x, qs[k2][1].y, qs[k2][1].z, qs[k2][1].w};
;             const unsigned x1w[4] = {qr[k2].x, qr[k2].y, qr[k2].z, qr[k2].w}, x2w[4] = {qr[k2 + 2].x, qr[k2 + 2].y, qr[k2 + 2].z, qr[k2 + 2].w};
;             unsigned o1[4], o2[4];
; #pragma unroll
;             for (int w2 = 0; w2 < 4; ++w2) { const float a1 = bf_lo(x1w[w2]), b1 = bf_hi(x1w[w2]), a2 = bf_lo(x2w[w2]), b2 = bf_hi(x2w[w2]);
;                 o1[w2] = cvt_pk_bf16(a1 * cs[2 * w2] - a2 * sn[2 * w2], b1 * cs[2 * w2 + 1] - b2 * sn[2 * w2 + 1]);
;                 o2[w2] = cvt_pk_bf16(a1 * sn[2 * w2] + a2 * cs[2 * w2], b1 * sn[2 * w2 + 1] + b2 * cs[2 * w2 + 1]); }
;             const u32x4 p1 = (u32x4){o1[0], o1[1], o1[2], o1[3]}, p2 = (u32x4){o2[0], o2[1], o2[2], o2[3]};
;             __builtin_memcpy(&qf[k2], &p1, 16); __builtin_memcpy(&qf[k2 + 2], &p2, 16);
;         }
;         bf16x8 pf[4];
; #pragma unroll
;         for (int s = 0; s < 4; ++s) {
;             f32x4 st2[2];
; #pragma unroll
;             for (int pp = 0; pp < 2; ++pp) {
;                 const bf16_t* kr = Kl + (32 * s + 8 * (fr >> 2) + 4 * pp + (fr & 3)) * LP + 8 * fq;
;                 f32x4 a = (f32x4){0.f, 0.f, 0.f, 0.f};
; #pragma unroll
;                 for (int ks = 0; ks < 4; ++ks) a = __builtin_amdgcn_mfma_f32_16x16x32_bf16(*(const bf16x8*)(kr + 32 * ks), qf[ks], a, 0, 0, 0);
	v_mov_b32_e32 v33, v193
	v_mov_b32_e32 v34, v194
	v_mov_b32_e32 v35, v195
	v_mov_b32_e32 v36, v196
	v_mov_b32_e32 v37, v197
	v_mov_b32_e32 v38, v198
	v_mov_b32_e32 v39, v199
	v_lshlrev_b32_e32 v44, 16, v4
	v_and_b32_e32 v45, 0xffff0000, v4
	v_lshl_add_u64 v[40:41], v[16:17], 0, v[154:155]
	v_lshlrev_b32_e32 v16, 16, v0
	v_and_b32_e32 v17, 0xffff0000, v0
	v_lshl_add_u64 v[42:43], v[40:41], 0, s[0:1]
	s_movk_i32 s0, 0x1000
	v_mul_f32_e32 v63, 0x3fb8aa3b, v23
	v_sub_u32_e32 v53, v86, v154
	v_pk_mul_f32 v[46:47], v[36:37], v[44:45]
	s_nop 0
	v_pk_fma_f32 v[46:47], v[28:29], v[16:17], v[46:47] neg_lo:[0,0,1] neg_hi:[0,0,1]
	v_pk_mul_f32 v[16:17], v[36:37], v[16:17]
	v_cvt_pk_bf16_f32 v4, v46, v47
	v_pk_fma_f32 v[16:17], v[28:29], v[44:45], v[16:17]
	v_lshlrev_b32_e32 v28, 16, v5
	v_and_b32_e32 v29, 0xffff0000, v5
	v_cvt_pk_bf16_f32 v0, v16, v17
	v_lshlrev_b32_e32 v16, 16, v1
	v_and_b32_e32 v17, 0xffff0000, v1
	v_pk_mul_f32 v[36:37], v[38:39], v[28:29]
	s_nop 0
	v_pk_fma_f32 v[36:37], v[30:31], v[16:17], v[36:37] neg_lo:[0,0,1] neg_hi:[0,0,1]
	v_pk_mul_f32 v[16:17], v[38:39], v[16:17]
	v_cvt_pk_bf16_f32 v5, v36, v37
	v_pk_fma_f32 v[16:17], v[30:31], v[28:29], v[16:17]
	v_lshlrev_b32_e32 v28, 16, v6
	v_and_b32_e32 v29, 0xffff0000, v6
	v_cvt_pk_bf16_f32 v1, v16, v17
	v_lshlrev_b32_e32 v16, 16, v2
	v_and_b32_e32 v17, 0xffff0000, v2
	v_pk_mul_f32 v[30:31], v[32:33], v[28:29]
	v_lshlrev_b32_e32 v36, 16, v12
	v_pk_fma_f32 v[30:31], v[24:25], v[16:17], v[30:31] neg_lo:[0,0,1] neg_hi:[0,0,1]
	v_pk_mul_f32 v[16:17], v[32:33], v[16:17]
	v_cvt_pk_bf16_f32 v6, v30, v31
	v_pk_fma_f32 v[16:17], v[24:25], v[28:29], v[16:17]
	v_lshlrev_b32_e32 v24, 16, v7
	v_and_b32_e32 v25, 0xffff0000, v7
	v_cvt_pk_bf16_f32 v2, v16, v17
	v_lshlrev_b32_e32 v16, 16, v3
	v_and_b32_e32 v17, 0xffff0000, v3
	v_pk_mul_f32 v[28:29], v[34:35], v[24:25]
	v_and_b32_e32 v37, 0xffff0000, v12
	v_pk_fma_f32 v[28:29], v[26:27], v[16:17], v[28:29] neg_lo:[0,0,1] neg_hi:[0,0,1]
	v_pk_mul_f32 v[16:17], v[34:35], v[16:17]
	v_cvt_pk_bf16_f32 v7, v28, v29
	v_pk_fma_f32 v[16:17], v[26:27], v[24:25], v[16:17]
	s_nop 0
	v_cvt_pk_bf16_f32 v3, v16, v17
	v_mov_b32_e32 v24, v200
	v_mov_b32_e32 v25, v201
	v_mov_b32_e32 v26, v202
	v_mov_b32_e32 v27, v203
	v_mov_b32_e32 v16, v204
	v_mov_b32_e32 v17, v205
	v_mov_b32_e32 v18, v206
	v_mov_b32_e32 v19, v207
	v_mov_b32_e32 v28, v208
	v_mov_b32_e32 v29, v209
	v_mov_b32_e32 v30, v210
	v_mov_b32_e32 v31, v211
	v_mov_b32_e32 v32, v212
	v_mov_b32_e32 v33, v213
	v_mov_b32_e32 v34, v214
	v_mov_b32_e32 v35, v215
	v_lshlrev_b32_e32 v20, 16, v8
	v_and_b32_e32 v21, 0xffff0000, v8
	s_waitcnt vmcnt(0)
	s_waitcnt lgkmcnt(0)
	s_barrier
	s_waitcnt vmcnt(0)
	v_pk_mul_f32 v[38:39], v[32:33], v[36:37]
	s_nop 0
	v_pk_fma_f32 v[38:39], v[16:17], v[20:21], v[38:39] neg_lo:[0,0,1] neg_hi:[0,0,1]
	v_pk_mul_f32 v[20:21], v[32:33], v[20:21]
	v_cvt_pk_bf16_f32 v12, v38, v39
	v_pk_fma_f32 v[16:17], v[16:17], v[36:37], v[20:21]
	v_lshlrev_b32_e32 v20, 16, v13
	v_and_b32_e32 v21, 0xffff0000, v13
	v_cvt_pk_bf16_f32 v8, v16, v17
	v_lshlrev_b32_e32 v16, 16, v9
	v_and_b32_e32 v17, 0xffff0000, v9
	v_pk_mul_f32 v[32:33], v[34:35], v[20:21]
	s_nop 0
	v_pk_fma_f32 v[32:33], v[18:19], v[16:17], v[32:33] neg_lo:[0,0,1] neg_hi:[0,0,1]
	v_pk_mul_f32 v[16:17], v[34:35], v[16:17]
	v_cvt_pk_bf16_f32 v13, v32, v33
	v_pk_fma_f32 v[16:17], v[18:19], v[20:21], v[16:17]
	v_lshlrev_b32_e32 v18, 16, v14
	v_and_b32_e32 v19, 0xffff0000, v14
	v_cvt_pk_bf16_f32 v9, v16, v17
	v_lshlrev_b32_e32 v16, 16, v10
	v_and_b32_e32 v17, 0xffff0000, v10
	v_pk_mul_f32 v[20:21], v[28:29], v[18:19]
	s_nop 0
	v_pk_fma_f32 v[20:21], v[24:25], v[16:17], v[20:21] neg_lo:[0,0,1] neg_hi:[0,0,1]
	v_pk_mul_f32 v[16:17], v[28:29], v[16:17]
	v_cvt_pk_bf16_f32 v14, v20, v21
	v_pk_fma_f32 v[16:17], v[24:25], v[18:19], v[16:17]
	v_lshlrev_b32_e32 v18, 16, v15
	v_cvt_pk_bf16_f32 v10, v16, v17
	v_add_co_u32_e32 v16, vcc, s0, v40
	v_and_b32_e32 v19, 0xffff0000, v15
	s_nop 0
	v_addc_co_u32_e32 v17, vcc, 0, v41, vcc
	global_load_dwordx2 v[78:79], v[16:17], off offset:512
	global_load_dwordx2 v[76:77], v[42:43], off offset:32
	global_load_dwordx2 v[74:75], v[42:43], off offset:64
	global_load_dwordx2 v[72:73], v[42:43], off offset:96
	global_load_dwordx2 v[70:71], v[42:43], off offset:128
	global_load_dwordx2 v[68:69], v[42:43], off offset:160
	global_load_dwordx2 v[66:67], v[42:43], off offset:192
	global_load_dwordx2 v[64:65], v[42:43], off offset:224
	v_lshlrev_b32_e32 v16, 16, v11
	v_and_b32_e32 v17, 0xffff0000, v11
	v_pk_mul_f32 v[20:21], v[30:31], v[18:19]
	s_movk_i32 s0, 0x58
	v_pk_fma_f32 v[20:21], v[26:27], v[16:17], v[20:21] neg_lo:[0,0,1] neg_hi:[0,0,1]
	v_pk_mul_f32 v[16:17], v[30:31], v[16:17]
	v_cvt_pk_bf16_f32 v15, v20, v21
	v_pk_fma_f32 v[16:17], v[26:27], v[18:19], v[16:17]
	s_waitcnt vmcnt(2)
	v_lshlrev_b32_e32 v142, 16, v69
	v_cvt_pk_bf16_f32 v11, v16, v17
	v_lshlrev_b32_e32 v16, 1, v22
	v_and_b32_e32 v17, 3, v22
	v_and_or_b32 v16, v16, 24, v17
	v_mul_u32_u24_e32 v16, 0x110, v16
	v_add3_u32 v52, 0, v62, v16
	ds_read_b128 v[16:19], v52
	ds_read_b128 v[20:23], v52 offset:64
	s_waitcnt lgkmcnt(1)
	v_mfma_f32_16x16x32_bf16 v[16:19], v[16:19], v[4:7], 0
	ds_read_b128 v[24:27], v52 offset:1152
	v_and_b32_e32 v143, 0xffff0000, v69
	v_lshlrev_b32_e32 v146, 16, v68
	s_waitcnt lgkmcnt(1)
	v_mfma_f32_16x16x32_bf16 v[16:19], v[20:23], v[12:15], v[16:19]
	ds_read_b128 v[20:23], v52 offset:128
	v_and_b32_e32 v147, 0xffff0000, v68
	s_waitcnt lgkmcnt(0)
	v_mfma_f32_16x16x32_bf16 v[16:19], v[20:23], v[0:3], v[16:19]
	ds_read_b128 v[20:23], v52 offset:192
	s_waitcnt lgkmcnt(0)
; __device__ __forceinline__ void ret_out(const bf16_t* proj, const float* cosT, const float* sinT, const float* decay, const float* gn_g, const float* gn_b,
;                         const bf16_t* states, bf16_t* mix, unsigned char* lds, int tid, int bx) {
;     ...
;         for (int s = 0; s < 4; ++s) {
;             f32x4 st2[2];
; #pragma unroll
;             for (int pp = 0; pp < 2; ++pp) {
;                 const bf16_t* kr = Kl + (32 * s + 8 * (fr >> 2) + 4 * pp + (fr & 3)) * LP + 8 * fq;
;                 f32x4 a = (f32x4){0.f, 0.f, 0.f, 0.f};
; #pragma unroll
;                 for (int ks = 0; ks < 4; ++ks) a = __builtin_amdgcn_mfma_f32_16x16x32_bf16(*(const bf16x8*)(kr + 32 * ks), qf[ks], a, 0, 0, 0);
; #pragma unroll
;                 for (int r = 0; r < 4; ++r) { const int sk = 32 * s + 8 * fq + 4 * pp + r, diff = cq - sk;
;                     const float df = (float)diff;
;                     const float dd = __builtin_amdgcn_exp2f(fminf(lgf2 * df, -lgb2 * df)) + fmaxf(1.0f - fabsf(df), 0.0f);
;                     a[r] *= dd * 0.08838834764831845f; }
;                 st2[pp] = a;
;             }
;             const u32x4 pw = (u32x4){cvt_pk_bf16(st2[0][0], st2[0][1]), cvt_pk_bf16(st2[0][2], st2[0][3]), cvt_pk_bf16(st2[1][0], st2[1][1]), cvt_pk_bf16(st2[1][2], st2[1][3])};
;             __builtin_memcpy(&pf[s], &pw, 16);
	v_mfma_f32_16x16x32_bf16 v[16:19], v[20:23], v[8:11], v[16:19]
	v_cvt_f32_i32_e32 v20, v53
	v_mul_f32_e32 v21, v87, v20
	v_mul_f32_e32 v22, v63, v20
	v_sub_f32_e64 v20, 1.0, |v20|
	v_max_f32_e32 v30, 0, v20
	v_xad_u32 v20, v154, -1, v86
	v_cvt_f32_i32_e32 v20, v20
	v_min_f32_e32 v21, v21, v22
	v_exp_f32_e32 v28, v21
	v_mul_f32_e32 v21, v87, v20
	v_mul_f32_e32 v22, v63, v20
	v_sub_f32_e64 v20, 1.0, |v20|
	v_max_f32_e32 v31, 0, v20
	v_add_u32_e32 v20, -2, v53
	v_cvt_f32_i32_e32 v20, v20
	v_min_f32_e32 v21, v21, v22
	v_exp_f32_e32 v29, v21
	v_mul_f32_e32 v21, v87, v20
	v_mul_f32_e32 v22, v63, v20
	v_sub_f32_e64 v20, 1.0, |v20|
	v_max_f32_e32 v34, 0, v20
	v_add_u32_e32 v20, -3, v53
	v_cvt_f32_i32_e32 v20, v20
	v_min_f32_e32 v21, v21, v22
	v_exp_f32_e32 v32, v21
	v_pk_add_f32 v[28:29], v[28:29], v[30:31]
	v_mul_f32_e32 v21, v87, v20
	v_mul_f32_e32 v22, v63, v20
	v_min_f32_e32 v21, v21, v22
	v_sub_f32_e64 v20, 1.0, |v20|
	v_exp_f32_e32 v33, v21
	v_max_f32_e32 v35, 0, v20
	ds_read_b128 v[20:23], v52 offset:1088
	s_waitcnt lgkmcnt(0)
	v_mfma_f32_16x16x32_bf16 v[20:23], v[20:23], v[4:7], 0
	v_mul_f32_e64 v28, v28, s54
	v_mul_f32_e64 v29, v29, s54
	v_pk_mul_f32 v[16:17], v[28:29], v[16:17]
	v_mfma_f32_16x16x32_bf16 v[20:23], v[24:27], v[12:15], v[20:23]
	ds_read_b128 v[24:27], v52 offset:1216
	v_pk_add_f32 v[28:29], v[32:33], v[34:35]
	v_cvt_pk_bf16_f32 v16, v16, v17
	s_waitcnt lgkmcnt(0)
	v_mfma_f32_16x16x32_bf16 v[20:23], v[24:27], v[0:3], v[20:23]
	ds_read_b128 v[24:27], v52 offset:1280
	v_pk_mul_f32 v[28:29], v[28:29], s[54:55] op_sel_hi:[1,0]
	s_waitcnt lgkmcnt(0)
	v_mfma_f32_16x16x32_bf16 v[20:23], v[24:27], v[8:11], v[20:23]
	v_add_u32_e32 v24, -4, v53
	v_cvt_f32_i32_e32 v25, v24
	v_pk_mul_f32 v[18:19], v[28:29], v[18:19]
	v_or_b32_e32 v28, 32, v154
	v_cvt_pk_bf16_f32 v17, v18, v19
	v_mul_f32_e32 v24, v87, v25
	v_mul_f32_e32 v26, v63, v25
	v_sub_f32_e64 v25, 1.0, |v25|
	v_min_f32_e32 v24, v24, v26
	v_max_f32_e32 v26, 0, v25
	v_add_u32_e32 v25, -5, v53
	v_cvt_f32_i32_e32 v27, v25
	v_exp_f32_e32 v24, v24
	v_mul_f32_e32 v25, v87, v27
	v_mul_f32_e32 v36, v63, v27
	v_min_f32_e32 v25, v25, v36
	v_add_u32_e32 v36, -6, v53
	v_cvt_f32_i32_e32 v37, v36
	v_exp_f32_e32 v25, v25
	v_sub_f32_e64 v27, 1.0, |v27|
	v_max_f32_e32 v27, 0, v27
	v_mul_f32_e32 v36, v87, v37
	v_mul_f32_e32 v38, v63, v37
	v_sub_f32_e64 v37, 1.0, |v37|
	v_min_f32_e32 v36, v36, v38
	v_max_f32_e32 v38, 0, v37
	v_add_u32_e32 v37, -7, v53
	v_cvt_f32_i32_e32 v39, v37
	v_exp_f32_e32 v36, v36
	v_pk_add_f32 v[18:19], v[24:25], v[26:27]
	ds_read_b128 v[24:27], v52 offset:8768
	v_mul_f32_e32 v37, v87, v39
	v_mul_f32_e32 v40, v63, v39
	v_min_f32_e32 v37, v37, v40
	v_exp_f32_e32 v37, v37
	v_sub_f32_e64 v39, 1.0, |v39|
	v_max_f32_e32 v39, 0, v39
	v_pk_mul_f32 v[18:19], v[18:19], s[54:55] op_sel_hi:[1,0]
	s_nop 0
	v_pk_mul_f32 v[18:19], v[18:19], v[20:21]
	v_pk_add_f32 v[20:21], v[36:37], v[38:39]
	v_cvt_pk_bf16_f32 v18, v18, v19
	v_pk_mul_f32 v[20:21], v[20:21], s[54:55] op_sel_hi:[1,0]
	s_nop 0
	v_pk_mul_f32 v[20:21], v[20:21], v[22:23]
	s_nop 0
	v_cvt_pk_bf16_f32 v19, v20, v21
	ds_read_b128 v[20:23], v52 offset:8704
	s_waitcnt lgkmcnt(0)
	v_mfma_f32_16x16x32_bf16 v[20:23], v[20:23], v[4:7], 0
	v_mfma_f32_16x16x32_bf16 v[20:23], v[24:27], v[12:15], v[20:23]
	ds_read_b128 v[24:27], v52 offset:8832
	s_waitcnt lgkmcnt(0)
	v_mfma_f32_16x16x32_bf16 v[20:23], v[24:27], v[0:3], v[20:23]
	ds_read_b128 v[24:27], v52 offset:8896
	s_waitcnt lgkmcnt(0)
	v_mfma_f32_16x16x32_bf16 v[20:23], v[24:27], v[8:11], v[20:23]
	v_sub_u32_e32 v24, v86, v28
	v_cvt_f32_i32_e32 v24, v24
	ds_read_b128 v[28:31], v52 offset:9856
	v_mul_f32_e32 v25, v87, v24
	v_mul_f32_e32 v26, v63, v24
	v_sub_f32_e64 v24, 1.0, |v24|
	v_max_f32_e32 v34, 0, v24
	v_subrev_u32_e32 v24, 33, v53
	v_cvt_f32_i32_e32 v24, v24
	v_min_f32_e32 v25, v25, v26
	v_exp_f32_e32 v32, v25
	v_mul_f32_e32 v25, v87, v24
	v_mul_f32_e32 v26, v63, v24
	v_sub_f32_e64 v24, 1.0, |v24|
	v_max_f32_e32 v35, 0, v24
	v_subrev_u32_e32 v24, 34, v53
	v_cvt_f32_i32_e32 v24, v24
	v_min_f32_e32 v25, v25, v26
	v_exp_f32_e32 v33, v25
	v_mul_f32_e32 v25, v87, v24
	v_mul_f32_e32 v26, v63, v24
	v_sub_f32_e64 v24, 1.0, |v24|
	v_max_f32_e32 v38, 0, v24
	v_subrev_u32_e32 v24, 35, v53
	v_cvt_f32_i32_e32 v24, v24
	v_min_f32_e32 v25, v25, v26
	v_exp_f32_e32 v36, v25
	v_pk_add_f32 v[32:33], v[32:33], v[34:35]
	v_mul_f32_e32 v25, v87, v24
	v_mul_f32_e32 v26, v63, v24
	v_min_f32_e32 v25, v25, v26
	v_sub_f32_e64 v24, 1.0, |v24|
	v_exp_f32_e32 v37, v25
	v_max_f32_e32 v39, 0, v24
	ds_read_b128 v[24:27], v52 offset:9792
	s_waitcnt lgkmcnt(0)
	v_mfma_f32_16x16x32_bf16 v[24:27], v[24:27], v[4:7], 0
	v_mul_f32_e64 v32, v32, s54
	v_mul_f32_e64 v33, v33, s54
	v_pk_mul_f32 v[20:21], v[32:33], v[20:21]
	v_mfma_f32_16x16x32_bf16 v[24:27], v[28:31], v[12:15], v[24:27]
	ds_read_b128 v[28:31], v52 offset:9920
	v_pk_add_f32 v[32:33], v[36:37], v[38:39]
	v_cvt_pk_bf16_f32 v20, v20, v21
	s_waitcnt lgkmcnt(0)
	v_mfma_f32_16x16x32_bf16 v[24:27], v[28:31], v[0:3], v[24:27]
	ds_read_b128 v[28:31], v52 offset:9984
	v_pk_mul_f32 v[32:33], v[32:33], s[54:55] op_sel_hi:[1,0]
	s_waitcnt lgkmcnt(0)
; __device__ __forceinline__ void ret_out(const bf16_t* proj, const float* cosT, const float* sinT, const float* decay, const float* gn_g, const float* gn_b,
;                         const bf16_t* states, bf16_t* mix, unsigned char* lds, int tid, int bx) {
;     ...
;         for (int s = 0; s < 4; ++s) {
;             f32x4 st2[2];
; #pragma unroll
;             for (int pp = 0; pp < 2; ++pp) {
;                 const bf16_t* kr = Kl + (32 * s + 8 * (fr >> 2) + 4 * pp + (fr & 3)) * LP + 8 * fq;
;                 f32x4 a = (f32x4){0.f, 0.f, 0.f, 0.f};
; #pragma unroll
;                 for (int ks = 0; ks < 4; ++ks) a = __builtin_amdgcn_mfma_f32_16x16x32_bf16(*(const bf16x8*)(kr + 32 * ks), qf[ks], a, 0, 0, 0);
; #pragma unroll
;                 for (int r = 0; r < 4; ++r) { const int sk = 32 * s + 8 * fq + 4 * pp + r, diff = cq - sk;
;                     const float df = (float)diff;
;                     const float dd = __builtin_amdgcn_exp2f(fminf(lgf2 * df, -lgb2 * df)) + fmaxf(1.0f - fabsf(df), 0.0f);
;                     a[r] *= dd * 0.08838834764831845f; }
;                 st2[pp] = a;
;             }
;             const u32x4 pw = (u32x4){cvt_pk_bf16(st2[0][0], st2[0][1]), cvt_pk_bf16(st2[0][2], st2[0][3]), cvt_pk_bf16(st2[1][0], st2[1][1]), cvt_pk_bf16(st2[1][2], st2[1][3])};
;             __builtin_memcpy(&pf[s], &pw, 16);
	v_mfma_f32_16x16x32_bf16 v[24:27], v[28:31], v[8:11], v[24:27]
	v_subrev_u32_e32 v28, 36, v53
	v_cvt_f32_i32_e32 v29, v28
	v_pk_mul_f32 v[22:23], v[32:33], v[22:23]
	v_or_b32_e32 v32, 64, v154
	v_cvt_pk_bf16_f32 v21, v22, v23
	v_mul_f32_e32 v28, v87, v29
	v_mul_f32_e32 v30, v63, v29
	v_sub_f32_e64 v29, 1.0, |v29|
	v_min_f32_e32 v28, v28, v30
	v_max_f32_e32 v30, 0, v29
	v_subrev_u32_e32 v29, 37, v53
	v_cvt_f32_i32_e32 v31, v29
	v_exp_f32_e32 v28, v28
	v_mul_f32_e32 v29, v87, v31
	v_mul_f32_e32 v40, v63, v31
	v_min_f32_e32 v29, v29, v40
	v_subrev_u32_e32 v40, 38, v53
	v_cvt_f32_i32_e32 v41, v40
	v_exp_f32_e32 v29, v29
	v_sub_f32_e64 v31, 1.0, |v31|
	v_max_f32_e32 v31, 0, v31
	v_mul_f32_e32 v40, v87, v41
	v_mul_f32_e32 v42, v63, v41
	v_sub_f32_e64 v41, 1.0, |v41|
	v_min_f32_e32 v40, v40, v42
	v_max_f32_e32 v42, 0, v41
	v_subrev_u32_e32 v41, 39, v53
	v_cvt_f32_i32_e32 v43, v41
	v_exp_f32_e32 v40, v40
	v_pk_add_f32 v[22:23], v[28:29], v[30:31]
	ds_read_b128 v[28:31], v52 offset:17472
	v_mul_f32_e32 v41, v87, v43
	v_mul_f32_e32 v44, v63, v43
	v_min_f32_e32 v41, v41, v44
	v_exp_f32_e32 v41, v41
	v_sub_f32_e64 v43, 1.0, |v43|
	v_max_f32_e32 v43, 0, v43
	v_pk_mul_f32 v[22:23], v[22:23], s[54:55] op_sel_hi:[1,0]
	s_nop 0
	v_pk_mul_f32 v[22:23], v[22:23], v[24:25]
	v_pk_add_f32 v[24:25], v[40:41], v[42:43]
	v_cvt_pk_bf16_f32 v22, v22, v23
	v_pk_mul_f32 v[24:25], v[24:25], s[54:55] op_sel_hi:[1,0]
	s_nop 0
	v_pk_mul_f32 v[24:25], v[24:25], v[26:27]
	s_nop 0
	v_cvt_pk_bf16_f32 v23, v24, v25
	ds_read_b128 v[24:27], v52 offset:17408
	s_waitcnt lgkmcnt(0)
	v_mfma_f32_16x16x32_bf16 v[24:27], v[24:27], v[4:7], 0
	v_mfma_f32_16x16x32_bf16 v[24:27], v[28:31], v[12:15], v[24:27]
	ds_read_b128 v[28:31], v52 offset:17536
	s_waitcnt lgkmcnt(0)
	v_mfma_f32_16x16x32_bf16 v[24:27], v[28:31], v[0:3], v[24:27]
	ds_read_b128 v[28:31], v52 offset:17600
	s_waitcnt lgkmcnt(0)
	v_mfma_f32_16x16x32_bf16 v[24:27], v[28:31], v[8:11], v[24:27]
	v_sub_u32_e32 v28, v86, v32
	v_cvt_f32_i32_e32 v28, v28
	ds_read_b128 v[32:35], v52 offset:18560
	v_mul_f32_e32 v29, v87, v28
	v_mul_f32_e32 v30, v63, v28
	v_sub_f32_e64 v28, 1.0, |v28|
	v_max_f32_e32 v38, 0, v28
	v_add_u32_e32 v28, 0xffffffbf, v53
	v_cvt_f32_i32_e32 v28, v28
	v_min_f32_e32 v29, v29, v30
	v_exp_f32_e32 v36, v29
	v_mul_f32_e32 v29, v87, v28
	v_mul_f32_e32 v30, v63, v28
	v_sub_f32_e64 v28, 1.0, |v28|
	v_max_f32_e32 v39, 0, v28
	v_add_u32_e32 v28, 0xffffffbe, v53
	v_cvt_f32_i32_e32 v28, v28
	v_min_f32_e32 v29, v29, v30
	v_exp_f32_e32 v37, v29
	v_mul_f32_e32 v29, v87, v28
	v_mul_f32_e32 v30, v63, v28
	v_sub_f32_e64 v28, 1.0, |v28|
	v_max_f32_e32 v42, 0, v28
	v_add_u32_e32 v28, 0xffffffbd, v53
	v_cvt_f32_i32_e32 v28, v28
	v_min_f32_e32 v29, v29, v30
	v_exp_f32_e32 v40, v29
	v_pk_add_f32 v[36:37], v[36:37], v[38:39]
	v_mul_f32_e32 v29, v87, v28
	v_mul_f32_e32 v30, v63, v28
	v_min_f32_e32 v29, v29, v30
	v_sub_f32_e64 v28, 1.0, |v28|
	v_exp_f32_e32 v41, v29
	v_max_f32_e32 v43, 0, v28
	ds_read_b128 v[28:31], v52 offset:18496
	s_waitcnt lgkmcnt(0)
	v_mfma_f32_16x16x32_bf16 v[28:31], v[28:31], v[4:7], 0
	v_mul_f32_e64 v36, v36, s54
	v_mul_f32_e64 v37, v37, s54
	v_pk_mul_f32 v[24:25], v[36:37], v[24:25]
	v_mfma_f32_16x16x32_bf16 v[28:31], v[32:35], v[12:15], v[28:31]
	ds_read_b128 v[32:35], v52 offset:18624
	s_waitcnt lgkmcnt(0)
	v_mfma_f32_16x16x32_bf16 v[28:31], v[32:35], v[0:3], v[28:31]
	ds_read_b128 v[32:35], v52 offset:18688
	s_waitcnt lgkmcnt(0)
	v_mfma_f32_16x16x32_bf16 v[28:31], v[32:35], v[8:11], v[28:31]
	v_add_u32_e32 v32, 0xffffffbc, v53
	v_cvt_f32_i32_e32 v33, v32
	v_mul_f32_e32 v32, v87, v33
	v_mul_f32_e32 v34, v63, v33
	v_sub_f32_e64 v33, 1.0, |v33|
	v_min_f32_e32 v32, v32, v34
	v_max_f32_e32 v34, 0, v33
	v_add_u32_e32 v33, 0xffffffbb, v53
	v_cvt_f32_i32_e32 v35, v33
	v_exp_f32_e32 v32, v32
	v_mul_f32_e32 v33, v87, v35
	v_mul_f32_e32 v44, v63, v35
	v_min_f32_e32 v33, v33, v44
	v_add_u32_e32 v44, 0xffffffba, v53
	v_cvt_f32_i32_e32 v45, v44
	v_exp_f32_e32 v33, v33
	v_sub_f32_e64 v35, 1.0, |v35|
	v_max_f32_e32 v35, 0, v35
	v_mul_f32_e32 v44, v87, v45
	v_mul_f32_e32 v46, v63, v45
	v_sub_f32_e64 v45, 1.0, |v45|
	v_min_f32_e32 v44, v44, v46
	v_max_f32_e32 v46, 0, v45
	v_add_u32_e32 v45, 0xffffffb9, v53
	v_cvt_f32_i32_e32 v47, v45
	v_exp_f32_e32 v44, v44
	v_mul_f32_e32 v45, v87, v47
	v_mul_f32_e32 v48, v63, v47
	v_min_f32_e32 v45, v45, v48
	v_cvt_pk_bf16_f32 v48, v24, v25
	v_pk_add_f32 v[24:25], v[40:41], v[42:43]
	v_exp_f32_e32 v45, v45
	v_pk_mul_f32 v[24:25], v[24:25], s[54:55] op_sel_hi:[1,0]
	v_sub_f32_e64 v47, 1.0, |v47|
	v_pk_mul_f32 v[24:25], v[24:25], v[26:27]
	v_max_f32_e32 v47, 0, v47
	v_cvt_pk_bf16_f32 v49, v24, v25
	v_pk_add_f32 v[24:25], v[32:33], v[34:35]
	v_or_b32_e32 v32, 0x60, v154
	v_pk_mul_f32 v[24:25], v[24:25], s[54:55] op_sel_hi:[1,0]
	s_nop 0
	v_pk_mul_f32 v[24:25], v[24:25], v[28:29]
	s_nop 0
	v_cvt_pk_bf16_f32 v50, v24, v25
	v_pk_add_f32 v[24:25], v[44:45], v[46:47]
	s_nop 0
	v_pk_mul_f32 v[24:25], v[24:25], s[54:55] op_sel_hi:[1,0]
	s_nop 0
	v_pk_mul_f32 v[24:25], v[24:25], v[30:31]
	ds_read_b128 v[28:31], v52 offset:26176
	v_cvt_pk_bf16_f32 v51, v24, v25
	ds_read_b128 v[24:27], v52 offset:26112
	s_waitcnt lgkmcnt(0)
	v_mfma_f32_16x16x32_bf16 v[24:27], v[24:27], v[4:7], 0
	v_mfma_f32_16x16x32_bf16 v[24:27], v[28:31], v[12:15], v[24:27]
	ds_read_b128 v[28:31], v52 offset:26240
	s_waitcnt lgkmcnt(0)
	v_mfma_f32_16x16x32_bf16 v[24:27], v[28:31], v[0:3], v[24:27]
	ds_read_b128 v[28:31], v52 offset:26304
	s_waitcnt lgkmcnt(0)
; __device__ __forceinline__ void ret_out(const bf16_t* proj, const float* cosT, const float* sinT, const float* decay, const float* gn_g, const float* gn_b,
;                         const bf16_t* states, bf16_t* mix, unsigned char* lds, int tid, int bx) {
;     ...
;         for (int s = 0; s < 4; ++s) {
;             f32x4 st2[2];
; #pragma unroll
;             for (int pp = 0; pp < 2; ++pp) {
;                 const bf16_t* kr = Kl + (32 * s + 8 * (fr >> 2) + 4 * pp + (fr & 3)) * LP + 8 * fq;
;                 f32x4 a = (f32x4){0.f, 0.f, 0.f, 0.f};
; #pragma unroll
;                 for (int ks = 0; ks < 4; ++ks) a = __builtin_amdgcn_mfma_f32_16x16x32_bf16(*(const bf16x8*)(kr + 32 * ks), qf[ks], a, 0, 0, 0);
; #pragma unroll
;                 for (int r = 0; r < 4; ++r) { const int sk = 32 * s + 8 * fq + 4 * pp + r, diff = cq - sk;
;                     const float df = (float)diff;
;                     const float dd = __builtin_amdgcn_exp2f(fminf(lgf2 * df, -lgb2 * df)) + fmaxf(1.0f - fabsf(df), 0.0f);
;                     a[r] *= dd * 0.08838834764831845f; }
;                 st2[pp] = a;
;             }
;             const u32x4 pw = (u32x4){cvt_pk_bf16(st2[0][0], st2[0][1]), cvt_pk_bf16(st2[0][2], st2[0][3]), cvt_pk_bf16(st2[1][0], st2[1][1]), cvt_pk_bf16(st2[1][2], st2[1][3])};
;             __builtin_memcpy(&pf[s], &pw, 16);
;         }
;         f32x4 acc[8];
; #pragma unroll
;         for (int e8 = 0; e8 < 8; ++e8) acc[e8] = (f32x4){0.f, 0.f, 0.f, 0.f};
; #pragma unroll
;         for (int s = 0; s < 4; ++s)
; #pragma unroll
;             for (int e8 = 0; e8 < 8; ++e8) acc[e8] = __builtin_amdgcn_mfma_f32_16x16x32_bf16(*(const bf16x8*)(Vl + (16 * e8 + fr) * LP + ((32 * s + 8 * fq) ^ ((e8 & 3) << 4))), pf[s], acc[e8], 0, 0, 0);
	v_mfma_f32_16x16x32_bf16 v[24:27], v[28:31], v[8:11], v[24:27]
	v_sub_u32_e32 v28, v86, v32
	v_cvt_f32_i32_e32 v28, v28
	ds_read_b128 v[32:35], v52 offset:27264
	v_mul_f32_e32 v29, v87, v28
	v_mul_f32_e32 v30, v63, v28
	v_sub_f32_e64 v28, 1.0, |v28|
	v_max_f32_e32 v38, 0, v28
	v_add_u32_e32 v28, 0xffffff9f, v53
	v_cvt_f32_i32_e32 v28, v28
	v_min_f32_e32 v29, v29, v30
	v_exp_f32_e32 v36, v29
	v_mul_f32_e32 v29, v87, v28
	v_mul_f32_e32 v30, v63, v28
	v_sub_f32_e64 v28, 1.0, |v28|
	v_max_f32_e32 v39, 0, v28
	v_add_u32_e32 v28, 0xffffff9e, v53
	v_cvt_f32_i32_e32 v28, v28
	v_min_f32_e32 v29, v29, v30
	v_exp_f32_e32 v37, v29
	v_mul_f32_e32 v29, v87, v28
	v_mul_f32_e32 v30, v63, v28
	v_sub_f32_e64 v28, 1.0, |v28|
	v_max_f32_e32 v42, 0, v28
	v_add_u32_e32 v28, 0xffffff9d, v53
	v_cvt_f32_i32_e32 v28, v28
	v_min_f32_e32 v29, v29, v30
	v_exp_f32_e32 v40, v29
	v_pk_add_f32 v[36:37], v[36:37], v[38:39]
	v_mul_f32_e32 v29, v87, v28
	v_mul_f32_e32 v30, v63, v28
	v_min_f32_e32 v29, v29, v30
	v_sub_f32_e64 v28, 1.0, |v28|
	v_exp_f32_e32 v41, v29
	v_max_f32_e32 v43, 0, v28
	ds_read_b128 v[28:31], v52 offset:27200
	s_waitcnt lgkmcnt(0)
	v_mfma_f32_16x16x32_bf16 v[28:31], v[28:31], v[4:7], 0
	v_mul_f32_e64 v36, v36, s54
	v_mul_f32_e64 v37, v37, s54
	v_pk_mul_f32 v[24:25], v[36:37], v[24:25]
	v_mfma_f32_16x16x32_bf16 v[28:31], v[32:35], v[12:15], v[28:31]
	ds_read_b128 v[32:35], v52 offset:27328
	v_pk_add_f32 v[36:37], v[40:41], v[42:43]
	v_cvt_pk_bf16_f32 v24, v24, v25
	s_waitcnt lgkmcnt(0)
	v_mfma_f32_16x16x32_bf16 v[28:31], v[32:35], v[0:3], v[28:31]
	ds_read_b128 v[32:35], v52 offset:27392
	v_pk_mul_f32 v[36:37], v[36:37], s[54:55] op_sel_hi:[1,0]
	s_waitcnt lgkmcnt(0)
	v_mfma_f32_16x16x32_bf16 v[28:31], v[32:35], v[8:11], v[28:31]
	v_add_u32_e32 v32, 0xffffff9c, v53
	v_cvt_f32_i32_e32 v33, v32
	v_pk_mul_f32 v[26:27], v[36:37], v[26:27]
	v_mul_f32_e32 v32, v87, v33
	v_mul_f32_e32 v34, v63, v33
	v_sub_f32_e64 v33, 1.0, |v33|
	v_min_f32_e32 v32, v32, v34
	v_max_f32_e32 v34, 0, v33
	v_add_u32_e32 v33, 0xffffff9b, v53
	v_cvt_f32_i32_e32 v35, v33
	v_exp_f32_e32 v32, v32
	v_cvt_pk_bf16_f32 v25, v26, v27
	v_mul_f32_e32 v33, v87, v35
	v_mul_f32_e32 v44, v63, v35
	v_min_f32_e32 v33, v33, v44
	v_add_u32_e32 v44, 0xffffff9a, v53
	v_cvt_f32_i32_e32 v45, v44
	v_exp_f32_e32 v33, v33
	v_sub_f32_e64 v35, 1.0, |v35|
	v_max_f32_e32 v35, 0, v35
	v_mul_f32_e32 v44, v87, v45
	v_mul_f32_e32 v46, v63, v45
	v_sub_f32_e64 v45, 1.0, |v45|
	v_min_f32_e32 v44, v44, v46
	v_max_f32_e32 v46, 0, v45
	v_add_u32_e32 v45, 0xffffff99, v53
	v_cvt_f32_i32_e32 v47, v45
	v_exp_f32_e32 v44, v44
	v_pk_add_f32 v[26:27], v[32:33], v[34:35]
	v_bitop3_b32 v53, v154, s0, v180 bitop3:0xc8
	v_mul_f32_e32 v45, v87, v47
	v_mul_f32_e32 v52, v63, v47
	v_min_f32_e32 v45, v45, v52
	v_exp_f32_e32 v45, v45
	v_sub_f32_e64 v47, 1.0, |v47|
	v_max_f32_e32 v47, 0, v47
	v_pk_mul_f32 v[26:27], v[26:27], s[54:55] op_sel_hi:[1,0]
	v_mad_u32_u24 v52, v83, s52, 0
	v_pk_mul_f32 v[26:27], v[26:27], v[28:29]
	v_pk_add_f32 v[28:29], v[44:45], v[46:47]
	v_add_u32_e32 v89, v52, v62
	v_pk_mul_f32 v[28:29], v[28:29], s[54:55] op_sel_hi:[1,0]
	v_xad_u32 v88, v62, 32, v52
	v_pk_mul_f32 v[28:29], v[28:29], v[30:31]
	v_cvt_pk_bf16_f32 v26, v26, v27
	v_cvt_pk_bf16_f32 v27, v28, v29
	ds_read_b128 v[28:31], v89 offset:34816
	ds_read_b128 v[36:39], v89 offset:43584
	ds_read_b128 v[32:35], v88 offset:39168
	ds_read_b128 v[40:43], v88 offset:47936
	ds_read_b128 v[44:47], v89 offset:52224
	ds_read_b128 v[90:93], v89 offset:60992
	ds_read_b128 v[54:57], v88 offset:56576
	ds_read_b128 v[94:97], v88 offset:65344
	s_waitcnt lgkmcnt(7)
	v_mfma_f32_16x16x32_bf16 v[28:31], v[28:31], v[16:19], 0
	s_lshl_b32 s0, s36, 9
	s_add_i32 s0, s0, 0
	s_cmpk_lt_i32 s49, 0x600
	s_waitcnt lgkmcnt(5)
	v_mfma_f32_16x16x32_bf16 v[32:35], v[32:35], v[16:19], 0
	v_mfma_f32_16x16x32_bf16 v[36:39], v[36:39], v[16:19], 0
	s_waitcnt lgkmcnt(4)
	v_mfma_f32_16x16x32_bf16 v[40:43], v[40:43], v[16:19], 0
	s_waitcnt lgkmcnt(3)
	v_mfma_f32_16x16x32_bf16 v[44:47], v[44:47], v[16:19], 0
	s_waitcnt lgkmcnt(1)
	v_mfma_f32_16x16x32_bf16 v[54:57], v[54:57], v[16:19], 0
	v_mfma_f32_16x16x32_bf16 v[90:93], v[90:93], v[16:19], 0
	s_waitcnt lgkmcnt(0)
	v_mfma_f32_16x16x32_bf16 v[16:19], v[94:97], v[16:19], 0
	ds_read_b128 v[94:97], v89 offset:34880
	s_waitcnt lgkmcnt(0)
	v_mfma_f32_16x16x32_bf16 v[28:31], v[94:97], v[20:23], v[28:31]
	ds_read_b128 v[94:97], v88 offset:39232
	s_waitcnt lgkmcnt(0)
	v_mfma_f32_16x16x32_bf16 v[32:35], v[94:97], v[20:23], v[32:35]
	ds_read_b128 v[94:97], v89 offset:43520
	s_waitcnt lgkmcnt(0)
	v_mfma_f32_16x16x32_bf16 v[36:39], v[94:97], v[20:23], v[36:39]
	ds_read_b128 v[94:97], v88 offset:47872
	s_waitcnt lgkmcnt(0)
	v_mfma_f32_16x16x32_bf16 v[40:43], v[94:97], v[20:23], v[40:43]
	ds_read_b128 v[94:97], v89 offset:52288
	s_waitcnt lgkmcnt(0)
	v_mfma_f32_16x16x32_bf16 v[44:47], v[94:97], v[20:23], v[44:47]
	ds_read_b128 v[94:97], v88 offset:56640
	s_waitcnt lgkmcnt(0)
	v_mfma_f32_16x16x32_bf16 v[54:57], v[94:97], v[20:23], v[54:57]
	ds_read_b128 v[94:97], v89 offset:60928
	s_waitcnt lgkmcnt(0)
	v_mfma_f32_16x16x32_bf16 v[90:93], v[94:97], v[20:23], v[90:93]
	ds_read_b128 v[94:97], v88 offset:65280
	s_waitcnt lgkmcnt(0)
	v_mfma_f32_16x16x32_bf16 v[16:19], v[94:97], v[20:23], v[16:19]
	ds_read_b128 v[20:23], v89 offset:34944
	s_waitcnt lgkmcnt(0)
	v_mfma_f32_16x16x32_bf16 v[20:23], v[20:23], v[48:51], v[28:31]
	s_nop 2
	ds_read_b128 v[28:31], v88 offset:39296
	s_waitcnt lgkmcnt(0)
	v_mfma_f32_16x16x32_bf16 v[94:97], v[28:31], v[48:51], v[32:35]
	ds_read_b128 v[28:31], v89 offset:43712
	s_nop 1
	ds_read_b128 v[32:35], v88 offset:48064
	s_waitcnt lgkmcnt(1)
; __device__ __forceinline__ void ret_out(const bf16_t* proj, const float* cosT, const float* sinT, const float* decay, const float* gn_g, const float* gn_b,
;                         const bf16_t* states, bf16_t* mix, unsigned char* lds, int tid, int bx) {
;     ...
; #pragma unroll
;         for (int s = 0; s < 4; ++s)
; #pragma unroll
;             for (int e8 = 0; e8 < 8; ++e8) acc[e8] = __builtin_amdgcn_mfma_f32_16x16x32_bf16(*(const bf16x8*)(Vl + (16 * e8 + fr) * LP + ((32 * s + 8 * fq) ^ ((e8 & 3) << 4))), pf[s], acc[e8], 0, 0, 0);
; #pragma unroll
;         for (int dir = 0; dir < 2; ++dir) {
;             const unsigned char* sl = lds + ST_OFF + dir * 32768 + fr * 256;
;             const float sc = dir == 0 ? __builtin_amdgcn_exp2f(lgf2 * (float)(cq + 1)) : __builtin_amdgcn_exp2f(lgb2 * (float)(128 - cq));
; #pragma unroll
;             for (int e8 = 0; e8 < 8; ++e8) {
;                 f32x4 a2 = (f32x4){0.f, 0.f, 0.f, 0.f};
; #pragma unroll
;                 for (int ks = 0; ks < 4; ++ks) a2 = __builtin_amdgcn_mfma_f32_16x16x32_bf16(*(const bf16x8*)(sl + e8 * 4096 + (((4 * ks + fq) ^ fr) << 4)), qf[ks], a2, 0, 0, 0);
;                 acc[e8] += a2 * sc;
;             }
	v_mfma_f32_16x16x32_bf16 v[28:31], v[28:31], v[48:51], v[36:39]
	s_nop 2
	ds_read_b128 v[36:39], v89 offset:52352
	s_waitcnt lgkmcnt(1)
	v_mfma_f32_16x16x32_bf16 v[32:35], v[32:35], v[48:51], v[40:43]
	s_nop 2
	ds_read_b128 v[40:43], v88 offset:56704
	s_waitcnt lgkmcnt(1)
	v_mfma_f32_16x16x32_bf16 v[36:39], v[36:39], v[48:51], v[44:47]
	s_nop 2
	ds_read_b128 v[44:47], v89 offset:61120
	s_waitcnt lgkmcnt(1)
	v_mfma_f32_16x16x32_bf16 v[40:43], v[40:43], v[48:51], v[54:57]
	s_nop 2
	ds_read_b128 v[54:57], v88 offset:65472
	s_waitcnt lgkmcnt(1)
	v_mfma_f32_16x16x32_bf16 v[44:47], v[44:47], v[48:51], v[90:93]
	s_nop 2
	v_lshl_add_u32 v90, v53, 1, v52
	s_waitcnt lgkmcnt(0)
	v_mfma_f32_16x16x32_bf16 v[48:51], v[54:57], v[48:51], v[16:19]
	ds_read_b128 v[52:55], v90 offset:43520
	s_nop 1
	ds_read_b128 v[16:19], v89 offset:35008
	s_waitcnt lgkmcnt(0)
	v_mfma_f32_16x16x32_bf16 v[20:23], v[16:19], v[24:27], v[20:23]
	ds_read_b128 v[16:19], v88 offset:39360
	v_mfma_f32_16x16x32_bf16 v[56:59], v[52:55], v[24:27], v[28:31]
	s_nop 2
	ds_read_b128 v[28:31], v88 offset:48000
	s_waitcnt lgkmcnt(0)
	v_mfma_f32_16x16x32_bf16 v[52:55], v[28:31], v[24:27], v[32:35]
	ds_read_b128 v[28:31], v89 offset:52416
	s_waitcnt lgkmcnt(0)
	v_mfma_f32_16x16x32_bf16 v[36:39], v[28:31], v[24:27], v[36:39]
	ds_read_b128 v[28:31], v88 offset:56768
	s_waitcnt lgkmcnt(0)
	v_mfma_f32_16x16x32_bf16 v[32:35], v[28:31], v[24:27], v[40:43]
	ds_read_b128 v[28:31], v90 offset:60928
	s_nop 1
	ds_read_b128 v[40:43], v88 offset:65408
	v_mfma_f32_16x16x32_bf16 v[16:19], v[16:19], v[24:27], v[94:97]
	s_waitcnt lgkmcnt(1)
	v_mfma_f32_16x16x32_bf16 v[28:31], v[28:31], v[24:27], v[44:47]
	s_waitcnt lgkmcnt(0)
	v_mfma_f32_16x16x32_bf16 v[24:27], v[40:43], v[24:27], v[48:51]
	v_lshl_add_u32 v41, v83, 8, s55
	v_sub_u32_e32 v40, 0x80, v86
	v_bitop3_b32 v43, v85, v83, 3 bitop3:0x6c
	v_cvt_f32_i32_e32 v40, v40
	v_lshl_add_u32 v43, v43, 4, v41
	ds_read_b128 v[44:47], v43
	v_bitop3_b32 v48, v84, v83, 4 bitop3:0x36
	v_mul_f32_e64 v40, -v63, v40
	v_lshl_add_u32 v63, v48, 4, v41
	ds_read_b128 v[48:51], v63
	s_waitcnt lgkmcnt(1)
	v_mfma_f32_16x16x32_bf16 v[44:47], v[44:47], v[4:7], 0
	v_exp_f32_e32 v42, v40
	v_add_u32_e32 v40, 1, v86
	v_cvt_f32_i32_e32 v40, v40
	s_waitcnt lgkmcnt(0)
	v_mfma_f32_16x16x32_bf16 v[44:47], v[48:51], v[12:15], v[44:47]
	v_bitop3_b32 v48, v84, v83, 8 bitop3:0x36
	v_lshl_add_u32 v100, v48, 4, v41
	ds_read_b128 v[48:51], v100
	s_waitcnt lgkmcnt(0)
	v_mfma_f32_16x16x32_bf16 v[44:47], v[48:51], v[0:3], v[44:47]
	v_bitop3_b32 v48, v84, v83, 12 bitop3:0x36
	v_lshl_add_u32 v83, v48, 4, v41
	ds_read_b128 v[48:51], v83
	v_mul_f32_e32 v40, v87, v40
	v_exp_f32_e32 v40, v40
	s_waitcnt lgkmcnt(0)
	v_mfma_f32_16x16x32_bf16 v[44:47], v[48:51], v[8:11], v[44:47]
	s_nop 7
	v_pk_fma_f32 v[48:49], v[40:41], v[46:47], v[22:23] op_sel_hi:[0,1,1]
	v_pk_fma_f32 v[50:51], v[40:41], v[44:45], v[20:21] op_sel_hi:[0,1,1]
	ds_read_b128 v[20:23], v43 offset:4096
	ds_read_b128 v[44:47], v63 offset:4096
	s_waitcnt lgkmcnt(1)
	v_mfma_f32_16x16x32_bf16 v[20:23], v[20:23], v[4:7], 0
	s_waitcnt lgkmcnt(0)
	v_mfma_f32_16x16x32_bf16 v[20:23], v[44:47], v[12:15], v[20:23]
	ds_read_b128 v[44:47], v100 offset:4096
	s_waitcnt lgkmcnt(0)
	v_mfma_f32_16x16x32_bf16 v[20:23], v[44:47], v[0:3], v[20:23]
	ds_read_b128 v[44:47], v83 offset:4096
	s_waitcnt lgkmcnt(0)
	v_mfma_f32_16x16x32_bf16 v[20:23], v[44:47], v[8:11], v[20:23]
	s_nop 7
	v_pk_fma_f32 v[44:45], v[40:41], v[22:23], v[18:19] op_sel_hi:[0,1,1]
	v_pk_fma_f32 v[46:47], v[40:41], v[20:21], v[16:17] op_sel_hi:[0,1,1]
	ds_read_b128 v[16:19], v43 offset:8192
	ds_read_b128 v[20:23], v63 offset:8192
	s_waitcnt lgkmcnt(1)
	v_mfma_f32_16x16x32_bf16 v[16:19], v[16:19], v[4:7], 0
	s_waitcnt lgkmcnt(0)
	v_mfma_f32_16x16x32_bf16 v[16:19], v[20:23], v[12:15], v[16:19]
	ds_read_b128 v[20:23], v100 offset:8192
	s_waitcnt lgkmcnt(0)
	v_mfma_f32_16x16x32_bf16 v[16:19], v[20:23], v[0:3], v[16:19]
	ds_read_b128 v[20:23], v83 offset:8192
	s_waitcnt lgkmcnt(0)
	v_mfma_f32_16x16x32_bf16 v[16:19], v[20:23], v[8:11], v[16:19]
	ds_read_b128 v[20:23], v63 offset:12288
	s_nop 6
	v_pk_fma_f32 v[58:59], v[40:41], v[18:19], v[58:59] op_sel_hi:[0,1,1]
	v_pk_fma_f32 v[56:57], v[40:41], v[16:17], v[56:57] op_sel_hi:[0,1,1]
	ds_read_b128 v[16:19], v43 offset:12288
	s_waitcnt lgkmcnt(0)
	v_mfma_f32_16x16x32_bf16 v[16:19], v[16:19], v[4:7], 0
	v_mfma_f32_16x16x32_bf16 v[16:19], v[20:23], v[12:15], v[16:19]
	ds_read_b128 v[20:23], v100 offset:12288
	s_waitcnt lgkmcnt(0)
	v_mfma_f32_16x16x32_bf16 v[16:19], v[20:23], v[0:3], v[16:19]
	ds_read_b128 v[20:23], v83 offset:12288
	s_waitcnt lgkmcnt(0)
	v_mfma_f32_16x16x32_bf16 v[16:19], v[20:23], v[8:11], v[16:19]
	ds_read_b128 v[20:23], v63 offset:16384
	s_nop 6
	v_pk_fma_f32 v[54:55], v[40:41], v[18:19], v[54:55] op_sel_hi:[0,1,1]
	v_pk_fma_f32 v[52:53], v[40:41], v[16:17], v[52:53] op_sel_hi:[0,1,1]
	ds_read_b128 v[16:19], v43 offset:16384
	s_waitcnt lgkmcnt(0)
	v_mfma_f32_16x16x32_bf16 v[16:19], v[16:19], v[4:7], 0
	v_mfma_f32_16x16x32_bf16 v[16:19], v[20:23], v[12:15], v[16:19]
	ds_read_b128 v[20:23], v100 offset:16384
	s_waitcnt lgkmcnt(0)
	v_mfma_f32_16x16x32_bf16 v[16:19], v[20:23], v[0:3], v[16:19]
	ds_read_b128 v[20:23], v83 offset:16384
	s_waitcnt lgkmcnt(0)
	v_mfma_f32_16x16x32_bf16 v[16:19], v[20:23], v[8:11], v[16:19]
	ds_read_b128 v[20:23], v63 offset:20480
	s_nop 6
	v_pk_fma_f32 v[84:85], v[40:41], v[18:19], v[38:39] op_sel_hi:[0,1,1]
	v_pk_fma_f32 v[86:87], v[40:41], v[16:17], v[36:37] op_sel_hi:[0,1,1]
	ds_read_b128 v[16:19], v43 offset:20480
	s_waitcnt lgkmcnt(0)
; __device__ __forceinline__ void ret_out(const bf16_t* proj, const float* cosT, const float* sinT, const float* decay, const float* gn_g, const float* gn_b,
;                         const bf16_t* states, bf16_t* mix, unsigned char* lds, int tid, int bx) {
;     ...
;         for (int dir = 0; dir < 2; ++dir) {
;             const unsigned char* sl = lds + ST_OFF + dir * 32768 + fr * 256;
;             const float sc = dir == 0 ? __builtin_amdgcn_exp2f(lgf2 * (float)(cq + 1)) : __builtin_amdgcn_exp2f(lgb2 * (float)(128 - cq));
; #pragma unroll
;             for (int e8 = 0; e8 < 8; ++e8) {
;                 f32x4 a2 = (f32x4){0.f, 0.f, 0.f, 0.f};
; #pragma unroll
;                 for (int ks = 0; ks < 4; ++ks) a2 = __builtin_amdgcn_mfma_f32_16x16x32_bf16(*(const bf16x8*)(sl + e8 * 4096 + (((4 * ks + fq) ^ fr) << 4)), qf[ks], a2, 0, 0, 0);
;                 acc[e8] += a2 * sc;
;             }
;         }
	v_mfma_f32_16x16x32_bf16 v[16:19], v[16:19], v[4:7], 0
	v_mfma_f32_16x16x32_bf16 v[16:19], v[20:23], v[12:15], v[16:19]
	ds_read_b128 v[20:23], v100 offset:20480
	s_waitcnt lgkmcnt(0)
	v_mfma_f32_16x16x32_bf16 v[16:19], v[20:23], v[0:3], v[16:19]
	ds_read_b128 v[20:23], v83 offset:20480
	s_waitcnt lgkmcnt(0)
	v_mfma_f32_16x16x32_bf16 v[16:19], v[20:23], v[8:11], v[16:19]
	ds_read_b128 v[20:23], v63 offset:24576
	s_nop 6
	v_pk_fma_f32 v[88:89], v[40:41], v[18:19], v[34:35] op_sel_hi:[0,1,1]
	v_pk_fma_f32 v[90:91], v[40:41], v[16:17], v[32:33] op_sel_hi:[0,1,1]
	ds_read_b128 v[16:19], v43 offset:24576
	s_waitcnt lgkmcnt(0)
	v_mfma_f32_16x16x32_bf16 v[16:19], v[16:19], v[4:7], 0
	v_mfma_f32_16x16x32_bf16 v[16:19], v[20:23], v[12:15], v[16:19]
	ds_read_b128 v[20:23], v100 offset:24576
	s_waitcnt lgkmcnt(0)
	v_mfma_f32_16x16x32_bf16 v[16:19], v[20:23], v[0:3], v[16:19]
	ds_read_b128 v[20:23], v83 offset:24576
	s_waitcnt lgkmcnt(0)
	v_mfma_f32_16x16x32_bf16 v[16:19], v[20:23], v[8:11], v[16:19]
	ds_read_b128 v[20:23], v63 offset:28672
	s_nop 6
	v_pk_fma_f32 v[92:93], v[40:41], v[18:19], v[30:31] op_sel_hi:[0,1,1]
	v_pk_fma_f32 v[94:95], v[40:41], v[16:17], v[28:29] op_sel_hi:[0,1,1]
	ds_read_b128 v[16:19], v43 offset:28672
	s_waitcnt lgkmcnt(0)
	v_mfma_f32_16x16x32_bf16 v[16:19], v[16:19], v[4:7], 0
	v_mfma_f32_16x16x32_bf16 v[16:19], v[20:23], v[12:15], v[16:19]
	ds_read_b128 v[20:23], v100 offset:28672
	s_waitcnt lgkmcnt(0)
	v_mfma_f32_16x16x32_bf16 v[16:19], v[20:23], v[0:3], v[16:19]
	ds_read_b128 v[20:23], v83 offset:28672
	s_waitcnt lgkmcnt(0)
	v_mfma_f32_16x16x32_bf16 v[16:19], v[20:23], v[8:11], v[16:19]
	ds_read_b128 v[20:23], v63 offset:32768
	s_nop 6
	v_pk_fma_f32 v[96:97], v[40:41], v[18:19], v[26:27] op_sel_hi:[0,1,1]
	v_pk_fma_f32 v[98:99], v[40:41], v[16:17], v[24:25] op_sel_hi:[0,1,1]
	ds_read_b128 v[16:19], v43 offset:32768
	s_waitcnt lgkmcnt(0)
	v_mfma_f32_16x16x32_bf16 v[16:19], v[16:19], v[4:7], 0
	v_mfma_f32_16x16x32_bf16 v[16:19], v[20:23], v[12:15], v[16:19]
	ds_read_b128 v[20:23], v100 offset:32768
	s_waitcnt lgkmcnt(0)
	v_mfma_f32_16x16x32_bf16 v[16:19], v[20:23], v[0:3], v[16:19]
	ds_read_b128 v[20:23], v83 offset:32768
	s_waitcnt lgkmcnt(0)
	v_mfma_f32_16x16x32_bf16 v[16:19], v[20:23], v[8:11], v[16:19]
	ds_read_b128 v[20:23], v63 offset:36864
	s_nop 6
	v_pk_fma_f32 v[40:41], v[42:43], v[18:19], v[48:49] op_sel_hi:[0,1,1]
	v_pk_fma_f32 v[38:39], v[42:43], v[16:17], v[50:51] op_sel_hi:[0,1,1]
	ds_read_b128 v[16:19], v43 offset:36864
	s_waitcnt lgkmcnt(0)
	v_mfma_f32_16x16x32_bf16 v[16:19], v[16:19], v[4:7], 0
	ds_read_b128 v[48:51], v63 offset:57344
	v_mfma_f32_16x16x32_bf16 v[16:19], v[20:23], v[12:15], v[16:19]
	ds_read_b128 v[20:23], v100 offset:36864
	s_waitcnt lgkmcnt(0)
	v_mfma_f32_16x16x32_bf16 v[16:19], v[20:23], v[0:3], v[16:19]
	ds_read_b128 v[20:23], v83 offset:36864
	s_waitcnt lgkmcnt(0)
	v_mfma_f32_16x16x32_bf16 v[16:19], v[20:23], v[8:11], v[16:19]
	ds_read_b128 v[20:23], v63 offset:40960
	s_nop 6
	v_pk_fma_f32 v[36:37], v[42:43], v[18:19], v[44:45] op_sel_hi:[0,1,1]
	v_pk_fma_f32 v[34:35], v[42:43], v[16:17], v[46:47] op_sel_hi:[0,1,1]
	ds_read_b128 v[16:19], v43 offset:40960
	s_waitcnt lgkmcnt(0)
	v_mfma_f32_16x16x32_bf16 v[16:19], v[16:19], v[4:7], 0
	ds_read_b128 v[44:47], v63 offset:53248
	v_mfma_f32_16x16x32_bf16 v[16:19], v[20:23], v[12:15], v[16:19]
	ds_read_b128 v[20:23], v100 offset:40960
	s_waitcnt lgkmcnt(0)
	v_mfma_f32_16x16x32_bf16 v[16:19], v[20:23], v[0:3], v[16:19]
	ds_read_b128 v[20:23], v83 offset:40960
	s_waitcnt lgkmcnt(0)
	v_mfma_f32_16x16x32_bf16 v[16:19], v[20:23], v[8:11], v[16:19]
	ds_read_b128 v[20:23], v63 offset:45056
	s_nop 6
	v_pk_fma_f32 v[32:33], v[42:43], v[18:19], v[58:59] op_sel_hi:[0,1,1]
	v_pk_fma_f32 v[30:31], v[42:43], v[16:17], v[56:57] op_sel_hi:[0,1,1]
	ds_read_b128 v[16:19], v43 offset:45056
	s_waitcnt lgkmcnt(0)
	v_mfma_f32_16x16x32_bf16 v[16:19], v[16:19], v[4:7], 0
	v_lshlrev_b32_e32 v56, 16, v75
	v_and_b32_e32 v57, 0xffff0000, v75
	v_and_b32_e32 v75, 0xffff0000, v73
	v_mfma_f32_16x16x32_bf16 v[16:19], v[20:23], v[12:15], v[16:19]
	ds_read_b128 v[20:23], v100 offset:45056
	s_waitcnt lgkmcnt(0)
	v_mfma_f32_16x16x32_bf16 v[16:19], v[20:23], v[0:3], v[16:19]
	ds_read_b128 v[20:23], v83 offset:45056
	s_waitcnt lgkmcnt(0)
	v_mfma_f32_16x16x32_bf16 v[16:19], v[20:23], v[8:11], v[16:19]
	ds_read_b128 v[20:23], v63 offset:49152
	s_nop 6
	v_pk_fma_f32 v[28:29], v[42:43], v[18:19], v[54:55] op_sel_hi:[0,1,1]
	v_pk_fma_f32 v[26:27], v[42:43], v[16:17], v[52:53] op_sel_hi:[0,1,1]
	ds_read_b128 v[16:19], v43 offset:49152
	s_waitcnt lgkmcnt(0)
	v_mfma_f32_16x16x32_bf16 v[16:19], v[16:19], v[4:7], 0
	v_lshlrev_b32_e32 v52, 16, v77
	v_and_b32_e32 v53, 0xffff0000, v77
	v_mfma_f32_16x16x32_bf16 v[16:19], v[20:23], v[12:15], v[16:19]
	ds_read_b128 v[20:23], v100 offset:49152
	s_waitcnt lgkmcnt(0)
	v_mfma_f32_16x16x32_bf16 v[16:19], v[20:23], v[0:3], v[16:19]
	ds_read_b128 v[20:23], v83 offset:49152
	s_waitcnt lgkmcnt(0)
	v_mfma_f32_16x16x32_bf16 v[16:19], v[20:23], v[8:11], v[16:19]
	s_nop 7
	v_pk_fma_f32 v[24:25], v[42:43], v[18:19], v[84:85] op_sel_hi:[0,1,1]
	v_pk_fma_f32 v[22:23], v[42:43], v[16:17], v[86:87] op_sel_hi:[0,1,1]
	ds_read_b128 v[16:19], v43 offset:53248
	s_waitcnt lgkmcnt(0)
	v_mfma_f32_16x16x32_bf16 v[16:19], v[16:19], v[4:7], 0
	v_mfma_f32_16x16x32_bf16 v[16:19], v[44:47], v[12:15], v[16:19]
	ds_read_b128 v[44:47], v100 offset:53248
	s_waitcnt lgkmcnt(0)
	v_mfma_f32_16x16x32_bf16 v[16:19], v[44:47], v[0:3], v[16:19]
	ds_read_b128 v[44:47], v83 offset:53248
	s_waitcnt lgkmcnt(0)
; __device__ __forceinline__ float bf_lo(unsigned u) { return __uint_as_float(u << 16); }
; __device__ __forceinline__ float bf_hi(unsigned u) { return __uint_as_float(u & 0xffff0000u); }
; __device__ __forceinline__ float silu_f(float x) { return x * __builtin_amdgcn_rcpf(1.0f + __expf(-x)); }
; __device__ __forceinline__ void ret_out(const bf16_t* proj, const float* cosT, const float* sinT, const float* decay, const float* gn_g, const float* gn_b,
;                         const bf16_t* states, bf16_t* mix, unsigned char* lds, int tid, int bx) {
;     ...
;             for (int e8 = 0; e8 < 8; ++e8) {
;                 f32x4 a2 = (f32x4){0.f, 0.f, 0.f, 0.f};
; #pragma unroll
;                 for (int ks = 0; ks < 4; ++ks) a2 = __builtin_amdgcn_mfma_f32_16x16x32_bf16(*(const bf16x8*)(sl + e8 * 4096 + (((4 * ks + fq) ^ fr) << 4)), qf[ks], a2, 0, 0, 0);
;                 acc[e8] += a2 * sc;
;             }
;         }
;         float sm = 0.f;
; #pragma unroll
;         for (int e8 = 0; e8 < 8; ++e8) sm += (acc[e8][0] + acc[e8][1]) + (acc[e8][2] + acc[e8][3]);
;         sm += __shfl_xor(sm, 16); sm += __shfl_xor(sm, 32);
;         const float mu = sm * (1.0f / 128.0f);
;         float vs = 0.f;
; #pragma unroll
;         for (int e8 = 0; e8 < 8; ++e8)
; #pragma unroll
;             for (int r = 0; r < 4; ++r) { const float dlt = acc[e8][r] - mu; vs += dlt * dlt; }
;         vs += __shfl_xor(vs, 16); vs += __shfl_xor(vs, 32);
;         const float rstd = 1.0f / sqrtf(vs * (1.0f / 128.0f) + 1e-5f);
;         bf16_t* op = mix + (size_t)(b * SEQ + tq) * 1024 + h * 128 + 4 * fq;
; #pragma unroll
;         for (int e8 = 0; e8 < 8; ++e8) {
;             const u32x2 gw = gwv[e8];
;             const float4 gg = *(const float4*)(gnl + h * 128 + 16 * e8 + 4 * fq), gb = *(const float4*)(gnl + 768 + h * 128 + 16 * e8 + 4 * fq);
;             const float y0 = ((acc[e8][0] - mu) * rstd * gg.x + gb.x) * silu_f(bf_lo(gw.x));
;             const float y1 = ((acc[e8][1] - mu) * rstd * gg.y + gb.y) * silu_f(bf_hi(gw.x));
;             const float y2 = ((acc[e8][2] - mu) * rstd * gg.z + gb.z) * silu_f(bf_lo(gw.y));
;             const float y3 = ((acc[e8][3] - mu) * rstd * gg.w + gb.w) * silu_f(bf_hi(gw.y));
	v_mfma_f32_16x16x32_bf16 v[16:19], v[44:47], v[8:11], v[16:19]
	ds_read_b128 v[44:47], v43 offset:57344
	s_nop 6
	v_pk_fma_f32 v[20:21], v[42:43], v[18:19], v[88:89] op_sel_hi:[0,1,1]
	s_waitcnt lgkmcnt(0)
	v_mfma_f32_16x16x32_bf16 v[44:47], v[44:47], v[4:7], 0
	v_fma_f32 v18, v42, v16, v90
	v_fma_f32 v19, v42, v17, v91
	v_mfma_f32_16x16x32_bf16 v[44:47], v[48:51], v[12:15], v[44:47]
	ds_read_b128 v[48:51], v100 offset:57344
	s_waitcnt lgkmcnt(0)
	v_mfma_f32_16x16x32_bf16 v[44:47], v[48:51], v[0:3], v[44:47]
	ds_read_b128 v[48:51], v83 offset:57344
	s_waitcnt lgkmcnt(0)
	v_mfma_f32_16x16x32_bf16 v[44:47], v[48:51], v[8:11], v[44:47]
	s_nop 7
	v_pk_fma_f32 v[48:49], v[42:43], v[46:47], v[92:93] op_sel_hi:[0,1,1]
	v_pk_fma_f32 v[16:17], v[42:43], v[44:45], v[94:95] op_sel_hi:[0,1,1]
	ds_read_b128 v[44:47], v43 offset:61440
	s_waitcnt lgkmcnt(0)
	v_mfma_f32_16x16x32_bf16 v[4:7], v[44:47], v[4:7], 0
	ds_read_b128 v[44:47], v63 offset:61440
	s_waitcnt lgkmcnt(0)
	v_mfma_f32_16x16x32_bf16 v[4:7], v[44:47], v[12:15], v[4:7]
	ds_read_b128 v[12:15], v100 offset:61440
	s_waitcnt lgkmcnt(0)
	v_mfma_f32_16x16x32_bf16 v[0:3], v[12:15], v[0:3], v[4:7]
	s_nop 4
	ds_read_b128 v[4:7], v83 offset:61440
	s_waitcnt lgkmcnt(0)
	v_mfma_f32_16x16x32_bf16 v[0:3], v[4:7], v[8:11], v[0:3]
	v_mov_b32_e32 v4, v38
	v_mov_b32_e32 v5, v34
	v_mov_b32_e32 v6, v39
	v_mov_b32_e32 v7, v35
	v_pk_add_f32 v[4:5], v[4:5], v[6:7]
	v_mov_b32_e32 v6, v40
	v_mov_b32_e32 v7, v36
	v_mov_b32_e32 v8, v41
	v_mov_b32_e32 v9, v37
	v_pk_add_f32 v[6:7], v[6:7], v[8:9]
	v_mov_b32_e32 v8, v30
	v_pk_add_f32 v[4:5], v[4:5], v[6:7]
	v_pk_mov_b32 v[6:7], v[30:31], v[32:33] op_sel:[1,0]
	v_mov_b32_e32 v9, v33
	v_pk_add_f32 v[6:7], v[6:7], v[8:9]
	v_add_f32_e32 v4, 0, v4
	v_pk_add_f32 v[6:7], v[6:7], v[6:7] op_sel:[0,1] op_sel_hi:[1,0]
	v_add_f32_e32 v4, v4, v5
	v_add_f32_e32 v8, v26, v27
	v_add_f32_e32 v10, v28, v29
	v_mov_b32_e32 v5, v22
	v_mov_b32_e32 v7, v23
	v_mov_b32_e32 v9, v24
	v_mov_b32_e32 v11, v25
	v_pk_add_f32 v[4:5], v[4:5], v[6:7]
	v_pk_add_f32 v[6:7], v[8:9], v[10:11]
	v_mov_b32_e32 v8, v18
	v_pk_add_f32 v[4:5], v[4:5], v[6:7]
	v_pk_mov_b32 v[6:7], v[18:19], v[20:21] op_sel:[1,0]
	v_mov_b32_e32 v9, v21
	v_pk_add_f32 v[6:7], v[6:7], v[8:9]
	v_pk_fma_f32 v[2:3], v[42:43], v[2:3], v[96:97] op_sel_hi:[0,1,1]
	v_pk_fma_f32 v[0:1], v[42:43], v[0:1], v[98:99] op_sel_hi:[0,1,1]
	v_pk_add_f32 v[4:5], v[4:5], v[4:5] op_sel:[0,1] op_sel_hi:[1,0]
	v_pk_add_f32 v[6:7], v[6:7], v[6:7] op_sel:[0,1] op_sel_hi:[1,0]
	v_add_f32_e32 v8, v16, v17
	v_add_f32_e32 v10, v48, v49
	v_mov_b32_e32 v5, v0
	v_mov_b32_e32 v7, v1
	v_mov_b32_e32 v9, v2
	v_mov_b32_e32 v11, v3
	v_pk_add_f32 v[4:5], v[4:5], v[6:7]
	v_pk_add_f32 v[6:7], v[8:9], v[10:11]
	s_nop 0
	v_pk_add_f32 v[4:5], v[4:5], v[6:7]
	s_nop 0
	v_add_f32_e32 v4, v4, v5
	ds_bpermute_b32 v5, v61, v4
	s_waitcnt lgkmcnt(0)
	v_add_f32_e32 v4, v4, v5
	ds_bpermute_b32 v5, v82, v4
	s_waitcnt lgkmcnt(0)
	v_add_f32_e32 v4, v4, v5
	v_mul_f32_e32 v14, 0x3c000000, v4
	v_pk_add_f32 v[6:7], v[48:49], v[14:15] op_sel_hi:[1,0] neg_lo:[0,1] neg_hi:[0,1]
	v_pk_add_f32 v[4:5], v[0:1], v[14:15] op_sel_hi:[1,0] neg_lo:[0,1] neg_hi:[0,1]
	v_pk_add_f32 v[2:3], v[2:3], v[14:15] op_sel_hi:[1,0] neg_lo:[0,1] neg_hi:[0,1]
	v_add_u32_e32 v15, s0, v62
	v_lshlrev_b32_e32 v48, 16, v79
	v_add_u32_e32 v83, 0x21000, v15
	v_add_u32_e32 v148, 0x21c00, v15
	v_pk_add_f32 v[62:63], v[40:41], v[14:15] op_sel_hi:[1,0] neg_lo:[0,1] neg_hi:[0,1]
	v_mul_f32_e32 v15, 0xbfb8aa3b, v48
	v_exp_f32_e32 v15, v15
	v_and_b32_e32 v49, 0xffff0000, v79
	v_lshlrev_b64 v[0:1], 11, v[80:81]
	v_pk_mul_f32 v[80:81], v[62:63], v[62:63]
	v_add_f32_e32 v15, 1.0, v15
	v_rcp_f32_e32 v50, v15
	v_mul_f32_e32 v15, 0xbfb8aa3b, v49
	v_exp_f32_e32 v15, v15
	v_pk_mul_f32 v[8:9], v[6:7], v[6:7]
	v_pk_mul_f32 v[10:11], v[4:5], v[4:5]
	v_pk_mul_f32 v[12:13], v[2:3], v[2:3]
	v_add_f32_e32 v15, 1.0, v15
	v_pk_add_f32 v[86:87], v[38:39], v[14:15] op_sel_hi:[1,0] neg_lo:[0,1] neg_hi:[0,1]
	v_lshlrev_b32_e32 v38, 16, v78
	v_rcp_f32_e32 v51, v15
	v_mul_f32_e32 v15, 0xbfb8aa3b, v38
	v_exp_f32_e32 v15, v15
	v_and_b32_e32 v39, 0xffff0000, v78
	v_pk_mul_f32 v[84:85], v[50:51], v[48:49]
	v_pk_mul_f32 v[88:89], v[86:87], v[86:87]
	v_add_f32_e32 v15, 1.0, v15
	v_rcp_f32_e32 v48, v15
	v_mul_f32_e32 v15, 0xbfb8aa3b, v39
	v_exp_f32_e32 v15, v15
	v_add_f32_e32 v88, v88, v89
	v_add_f32_e32 v80, v80, v88
	v_add_f32_e32 v80, v81, v80
	v_add_f32_e32 v15, 1.0, v15
	v_rcp_f32_e32 v49, v15
	v_pk_add_f32 v[92:93], v[36:37], v[14:15] op_sel_hi:[1,0] neg_lo:[0,1] neg_hi:[0,1]
	v_mul_f32_e32 v15, 0xbfb8aa3b, v52
	v_exp_f32_e32 v15, v15
	v_pk_mul_f32 v[94:95], v[92:93], v[92:93]
	ds_read_b128 v[40:43], v83
	ds_read_b128 v[44:47], v148
	v_pk_mul_f32 v[90:91], v[48:49], v[38:39]
	v_add_f32_e32 v15, 1.0, v15
	v_rcp_f32_e32 v54, v15
	v_mul_f32_e32 v15, 0xbfb8aa3b, v53
	v_exp_f32_e32 v15, v15
	ds_read_b128 v[36:39], v83 offset:64
	ds_read_b128 v[48:51], v148 offset:64
	v_lshl_add_u64 v[0:1], s[42:43], 0, v[0:1]
	v_lshl_add_u64 v[0:1], v[0:1], 0, s[46:47]
	v_add_f32_e32 v15, 1.0, v15
	v_pk_add_f32 v[98:99], v[34:35], v[14:15] op_sel_hi:[1,0] neg_lo:[0,1] neg_hi:[0,1]
	v_lshlrev_b32_e32 v34, 16, v76
	v_rcp_f32_e32 v55, v15
	v_mul_f32_e32 v15, 0xbfb8aa3b, v34
	v_exp_f32_e32 v15, v15
	v_and_b32_e32 v35, 0xffff0000, v76
	v_pk_mul_f32 v[96:97], v[54:55], v[52:53]
	v_pk_mul_f32 v[100:101], v[98:99], v[98:99]
	v_add_f32_e32 v15, 1.0, v15
	v_rcp_f32_e32 v52, v15
	v_mul_f32_e32 v15, 0xbfb8aa3b, v35
	v_exp_f32_e32 v15, v15
	v_add_f32_e32 v80, v100, v80
	v_add_f32_e32 v80, v101, v80
	v_add_f32_e32 v80, v94, v80
	v_add_f32_e32 v15, 1.0, v15
	v_rcp_f32_e32 v53, v15
; __device__ __forceinline__ float bf_lo(unsigned u) { return __uint_as_float(u << 16); }
; __device__ __forceinline__ float bf_hi(unsigned u) { return __uint_as_float(u & 0xffff0000u); }
; __device__ __forceinline__ float silu_f(float x) { return x * __builtin_amdgcn_rcpf(1.0f + __expf(-x)); }
; __device__ __forceinline__ void ret_out(const bf16_t* proj, const float* cosT, const float* sinT, const float* decay, const float* gn_g, const float* gn_b,
;                         const bf16_t* states, bf16_t* mix, unsigned char* lds, int tid, int bx) {
;     ...
;         float sm = 0.f;
; #pragma unroll
;         for (int e8 = 0; e8 < 8; ++e8) sm += (acc[e8][0] + acc[e8][1]) + (acc[e8][2] + acc[e8][3]);
;         sm += __shfl_xor(sm, 16); sm += __shfl_xor(sm, 32);
;         const float mu = sm * (1.0f / 128.0f);
;         float vs = 0.f;
; #pragma unroll
;         for (int e8 = 0; e8 < 8; ++e8)
; #pragma unroll
;             for (int r = 0; r < 4; ++r) { const float dlt = acc[e8][r] - mu; vs += dlt * dlt; }
;         vs += __shfl_xor(vs, 16); vs += __shfl_xor(vs, 32);
;         const float rstd = 1.0f / sqrtf(vs * (1.0f / 128.0f) + 1e-5f);
;         bf16_t* op = mix + (size_t)(b * SEQ + tq) * 1024 + h * 128 + 4 * fq;
; #pragma unroll
;         for (int e8 = 0; e8 < 8; ++e8) {
;             const u32x2 gw = gwv[e8];
;             const float4 gg = *(const float4*)(gnl + h * 128 + 16 * e8 + 4 * fq), gb = *(const float4*)(gnl + 768 + h * 128 + 16 * e8 + 4 * fq);
;             const float y0 = ((acc[e8][0] - mu) * rstd * gg.x + gb.x) * silu_f(bf_lo(gw.x));
;             const float y1 = ((acc[e8][1] - mu) * rstd * gg.y + gb.y) * silu_f(bf_hi(gw.x));
;             const float y2 = ((acc[e8][2] - mu) * rstd * gg.z + gb.z) * silu_f(bf_lo(gw.y));
;             const float y3 = ((acc[e8][3] - mu) * rstd * gg.w + gb.w) * silu_f(bf_hi(gw.y));
	v_pk_add_f32 v[104:105], v[32:33], v[14:15] op_sel_hi:[1,0] neg_lo:[0,1] neg_hi:[0,1]
	v_mul_f32_e32 v15, 0xbfb8aa3b, v56
	v_exp_f32_e32 v15, v15
	v_add_f32_e32 v80, v95, v80
	v_pk_mul_f32 v[106:107], v[104:105], v[104:105]
	v_lshl_add_u64 v[0:1], v[0:1], 0, v[154:155]
	v_add_f32_e32 v15, 1.0, v15
	v_rcp_f32_e32 v58, v15
	v_mul_f32_e32 v15, 0xbfb8aa3b, v57
	v_exp_f32_e32 v15, v15
	v_pk_mul_f32 v[102:103], v[52:53], v[34:35]
	ds_read_b128 v[32:35], v83 offset:128
	ds_read_b128 v[52:55], v148 offset:128
	v_add_f32_e32 v15, 1.0, v15
	v_pk_add_f32 v[110:111], v[30:31], v[14:15] op_sel_hi:[1,0] neg_lo:[0,1] neg_hi:[0,1]
	v_lshlrev_b32_e32 v30, 16, v74
	v_rcp_f32_e32 v59, v15
	v_mul_f32_e32 v15, 0xbfb8aa3b, v30
	v_exp_f32_e32 v15, v15
	v_and_b32_e32 v31, 0xffff0000, v74
	v_pk_mul_f32 v[108:109], v[58:59], v[56:57]
	v_lshlrev_b32_e32 v74, 16, v73
	v_add_f32_e32 v15, 1.0, v15
	v_rcp_f32_e32 v56, v15
	v_mul_f32_e32 v15, 0xbfb8aa3b, v31
	v_exp_f32_e32 v15, v15
	v_pk_mul_f32 v[112:113], v[110:111], v[110:111]
	v_add_f32_e32 v15, 1.0, v15
	v_rcp_f32_e32 v57, v15
	v_pk_add_f32 v[116:117], v[28:29], v[14:15] op_sel_hi:[1,0] neg_lo:[0,1] neg_hi:[0,1]
	v_mul_f32_e32 v15, 0xbfb8aa3b, v74
	v_exp_f32_e32 v15, v15
	v_add_f32_e32 v80, v112, v80
	v_add_f32_e32 v80, v113, v80
	v_add_f32_e32 v80, v106, v80
	v_add_f32_e32 v15, 1.0, v15
	v_rcp_f32_e32 v76, v15
	v_mul_f32_e32 v15, 0xbfb8aa3b, v75
	v_exp_f32_e32 v15, v15
	v_add_f32_e32 v80, v107, v80
	v_pk_mul_f32 v[118:119], v[116:117], v[116:117]
	v_pk_mul_f32 v[114:115], v[56:57], v[30:31]
	v_add_f32_e32 v15, 1.0, v15
	v_pk_add_f32 v[122:123], v[26:27], v[14:15] op_sel_hi:[1,0] neg_lo:[0,1] neg_hi:[0,1]
	v_lshlrev_b32_e32 v26, 16, v72
	v_rcp_f32_e32 v77, v15
	v_mul_f32_e32 v15, 0xbfb8aa3b, v26
	v_exp_f32_e32 v15, v15
	v_and_b32_e32 v27, 0xffff0000, v72
	v_pk_mul_f32 v[120:121], v[76:77], v[74:75]
	v_lshlrev_b32_e32 v76, 16, v71
	v_add_f32_e32 v15, 1.0, v15
	v_rcp_f32_e32 v72, v15
	v_mul_f32_e32 v15, 0xbfb8aa3b, v27
	v_exp_f32_e32 v15, v15
	v_and_b32_e32 v77, 0xffff0000, v71
	v_pk_mul_f32 v[124:125], v[122:123], v[122:123]
	ds_read_b128 v[28:31], v83 offset:192
	ds_read_b128 v[56:59], v148 offset:192
	v_add_f32_e32 v15, 1.0, v15
	v_rcp_f32_e32 v73, v15
	v_pk_add_f32 v[128:129], v[24:25], v[14:15] op_sel_hi:[1,0] neg_lo:[0,1] neg_hi:[0,1]
	v_mul_f32_e32 v15, 0xbfb8aa3b, v76
	v_exp_f32_e32 v15, v15
	v_add_f32_e32 v80, v124, v80
	v_add_f32_e32 v80, v125, v80
	v_add_f32_e32 v80, v118, v80
	v_add_f32_e32 v15, 1.0, v15
	v_rcp_f32_e32 v78, v15
	v_mul_f32_e32 v15, 0xbfb8aa3b, v77
	v_exp_f32_e32 v15, v15
	v_add_f32_e32 v80, v119, v80
	v_pk_mul_f32 v[130:131], v[128:129], v[128:129]
	v_pk_mul_f32 v[126:127], v[72:73], v[26:27]
	v_add_f32_e32 v15, 1.0, v15
	v_pk_add_f32 v[134:135], v[22:23], v[14:15] op_sel_hi:[1,0] neg_lo:[0,1] neg_hi:[0,1]
	v_lshlrev_b32_e32 v22, 16, v70
	v_rcp_f32_e32 v79, v15
	v_mul_f32_e32 v15, 0xbfb8aa3b, v22
	v_exp_f32_e32 v15, v15
	v_and_b32_e32 v23, 0xffff0000, v70
	v_pk_mul_f32 v[136:137], v[134:135], v[134:135]
	ds_read_b128 v[24:27], v83 offset:256
	ds_read_b128 v[72:75], v148 offset:256
	v_add_f32_e32 v15, 1.0, v15
	v_rcp_f32_e32 v70, v15
	v_mul_f32_e32 v15, 0xbfb8aa3b, v23
	v_exp_f32_e32 v15, v15
	v_add_f32_e32 v80, v136, v80
	v_add_f32_e32 v80, v137, v80
	v_add_f32_e32 v80, v130, v80
	v_add_f32_e32 v15, 1.0, v15
	v_rcp_f32_e32 v71, v15
	v_pk_add_f32 v[138:139], v[20:21], v[14:15] op_sel_hi:[1,0] neg_lo:[0,1] neg_hi:[0,1]
	v_mul_f32_e32 v15, 0xbfb8aa3b, v142
	v_exp_f32_e32 v15, v15
	v_add_f32_e32 v80, v131, v80
	v_pk_mul_f32 v[140:141], v[138:139], v[138:139]
	v_pk_mul_f32 v[132:133], v[78:79], v[76:77]
	v_add_f32_e32 v15, 1.0, v15
	v_rcp_f32_e32 v144, v15
	v_mul_f32_e32 v15, 0xbfb8aa3b, v143
	v_exp_f32_e32 v15, v15
	v_pk_mul_f32 v[70:71], v[70:71], v[22:23]
	ds_read_b128 v[20:23], v83 offset:320
	ds_read_b128 v[76:79], v148 offset:320
	v_add_f32_e32 v15, 1.0, v15
	v_rcp_f32_e32 v145, v15
	v_pk_add_f32 v[18:19], v[18:19], v[14:15] op_sel_hi:[1,0] neg_lo:[0,1] neg_hi:[0,1]
	v_mul_f32_e32 v15, 0xbfb8aa3b, v146
	v_exp_f32_e32 v15, v15
	v_pk_mul_f32 v[142:143], v[144:145], v[142:143]
	v_pk_mul_f32 v[144:145], v[18:19], v[18:19]
	v_add_f32_e32 v15, 1.0, v15
	v_rcp_f32_e32 v68, v15
	v_mul_f32_e32 v15, 0xbfb8aa3b, v147
	v_exp_f32_e32 v15, v15
	v_add_f32_e32 v80, v144, v80
	v_add_f32_e32 v80, v145, v80
	v_add_f32_e32 v80, v140, v80
	v_add_f32_e32 v15, 1.0, v15
	v_pk_add_f32 v[16:17], v[16:17], v[14:15] op_sel_hi:[1,0] neg_lo:[0,1] neg_hi:[0,1]
	v_rcp_f32_e32 v69, v15
	v_pk_mul_f32 v[14:15], v[16:17], v[16:17]
	v_add_f32_e32 v80, v141, v80
	v_add_f32_e32 v14, v14, v80
	v_add_f32_e32 v14, v15, v14
	v_add_f32_e32 v8, v8, v14
	v_add_f32_e32 v8, v9, v8
	v_add_f32_e32 v8, v10, v8
	v_add_f32_e32 v8, v11, v8
	v_add_f32_e32 v8, v12, v8
	v_add_f32_e32 v8, v13, v8
	ds_bpermute_b32 v9, v61, v8
	v_pk_mul_f32 v[68:69], v[68:69], v[146:147]
	s_waitcnt lgkmcnt(0)
	v_add_f32_e32 v8, v8, v9
	ds_bpermute_b32 v9, v82, v8
	s_waitcnt lgkmcnt(0)
; __device__ __forceinline__ float bf_lo(unsigned u) { return __uint_as_float(u << 16); }
; __device__ __forceinline__ float bf_hi(unsigned u) { return __uint_as_float(u & 0xffff0000u); }
; __device__ __forceinline__ float silu_f(float x) { return x * __builtin_amdgcn_rcpf(1.0f + __expf(-x)); }
; __device__ __forceinline__ void ret_out(const bf16_t* proj, const float* cosT, const float* sinT, const float* decay, const float* gn_g, const float* gn_b,
;                         const bf16_t* states, bf16_t* mix, unsigned char* lds, int tid, int bx) {
;     ...
;         vs += __shfl_xor(vs, 16); vs += __shfl_xor(vs, 32);
;         const float rstd = 1.0f / sqrtf(vs * (1.0f / 128.0f) + 1e-5f);
;         bf16_t* op = mix + (size_t)(b * SEQ + tq) * 1024 + h * 128 + 4 * fq;
; #pragma unroll
;         for (int e8 = 0; e8 < 8; ++e8) {
;             const u32x2 gw = gwv[e8];
;             const float4 gg = *(const float4*)(gnl + h * 128 + 16 * e8 + 4 * fq), gb = *(const float4*)(gnl + 768 + h * 128 + 16 * e8 + 4 * fq);
;             const float y0 = ((acc[e8][0] - mu) * rstd * gg.x + gb.x) * silu_f(bf_lo(gw.x));
;             const float y1 = ((acc[e8][1] - mu) * rstd * gg.y + gb.y) * silu_f(bf_hi(gw.x));
;             const float y2 = ((acc[e8][2] - mu) * rstd * gg.z + gb.z) * silu_f(bf_lo(gw.y));
;             const float y3 = ((acc[e8][3] - mu) * rstd * gg.w + gb.w) * silu_f(bf_hi(gw.y));
;             u32x2 w; w.x = cvt_pk_bf16(y0, y1); w.y = cvt_pk_bf16(y2, y3);
;             *(u32x2*)(op + 16 * e8) = w;
;         }
;     }
	v_add_f32_e32 v8, v8, v9
	v_fmamk_f32 v8, v8, 0x3c000000, v175
	v_cmp_gt_f32_e32 vcc, s64, v8
	v_mul_f32_e32 v9, 0x4f800000, v8
	s_nop 0
	v_cndmask_b32_e32 v8, v8, v9, vcc
	v_sqrt_f32_e32 v9, v8
	s_nop 0
	v_add_u32_e32 v10, -1, v9
	v_fma_f32 v11, -v10, v9, v8
	v_cmp_ge_f32_e64 s[36:37], 0, v11
	v_add_u32_e32 v11, 1, v9
	s_nop 0
	v_cndmask_b32_e64 v10, v9, v10, s[36:37]
	v_fma_f32 v9, -v11, v9, v8
	v_cmp_lt_f32_e64 s[36:37], 0, v9
	s_nop 1
	v_cndmask_b32_e64 v9, v10, v11, s[36:37]
	v_mul_f32_e32 v10, 0x37800000, v9
	v_cndmask_b32_e32 v9, v9, v10, vcc
	v_cmp_class_f32_e32 vcc, v8, v176
	s_nop 1
	v_cndmask_b32_e32 v8, v9, v8, vcc
	v_div_scale_f32 v9, s[0:1], v8, v8, 1.0
	v_rcp_f32_e32 v10, v9
	s_nop 0
	v_fma_f32 v11, -v9, v10, 1.0
	v_fmac_f32_e32 v10, v11, v10
	v_div_scale_f32 v11, vcc, 1.0, v8, 1.0
	v_mul_f32_e32 v12, v11, v10
	v_fma_f32 v13, -v9, v12, v11
	v_fmac_f32_e32 v12, v13, v10
	v_fma_f32 v9, -v9, v12, v11
	v_div_fmas_f32 v9, v9, v10, v12
	v_div_fixup_f32 v80, v9, v8, 1.0
	v_pk_mul_f32 v[8:9], v[86:87], v[80:81] op_sel_hi:[1,0]
	v_pk_mul_f32 v[10:11], v[62:63], v[80:81] op_sel_hi:[1,0]
	v_pk_fma_f32 v[8:9], v[40:41], v[8:9], v[44:45]
	v_pk_fma_f32 v[10:11], v[42:43], v[10:11], v[46:47]
	v_pk_mul_f32 v[8:9], v[90:91], v[8:9]
	v_pk_mul_f32 v[10:11], v[84:85], v[10:11]
	v_cvt_pk_bf16_f32 v8, v8, v9
	v_cvt_pk_bf16_f32 v9, v10, v11
	global_store_dwordx2 v[0:1], v[8:9], off
	v_pk_mul_f32 v[8:9], v[98:99], v[80:81] op_sel_hi:[1,0]
	v_pk_mul_f32 v[10:11], v[92:93], v[80:81] op_sel_hi:[1,0]
	v_pk_fma_f32 v[8:9], v[36:37], v[8:9], v[48:49]
	v_pk_fma_f32 v[10:11], v[38:39], v[10:11], v[50:51]
	v_pk_mul_f32 v[8:9], v[102:103], v[8:9]
	v_pk_mul_f32 v[10:11], v[96:97], v[10:11]
	v_cvt_pk_bf16_f32 v8, v8, v9
	v_cvt_pk_bf16_f32 v9, v10, v11
	global_store_dwordx2 v[0:1], v[8:9], off offset:32
	v_pk_mul_f32 v[8:9], v[110:111], v[80:81] op_sel_hi:[1,0]
	v_pk_mul_f32 v[10:11], v[104:105], v[80:81] op_sel_hi:[1,0]
	v_pk_fma_f32 v[8:9], v[32:33], v[8:9], v[52:53]
	v_pk_fma_f32 v[10:11], v[34:35], v[10:11], v[54:55]
	v_pk_mul_f32 v[8:9], v[114:115], v[8:9]
	v_pk_mul_f32 v[10:11], v[108:109], v[10:11]
	v_cvt_pk_bf16_f32 v8, v8, v9
	v_cvt_pk_bf16_f32 v9, v10, v11
	global_store_dwordx2 v[0:1], v[8:9], off offset:64
	v_pk_mul_f32 v[8:9], v[122:123], v[80:81] op_sel_hi:[1,0]
	v_pk_mul_f32 v[10:11], v[116:117], v[80:81] op_sel_hi:[1,0]
	v_pk_fma_f32 v[8:9], v[28:29], v[8:9], v[56:57]
	v_pk_fma_f32 v[10:11], v[30:31], v[10:11], v[58:59]
	v_pk_mul_f32 v[8:9], v[126:127], v[8:9]
	v_pk_mul_f32 v[10:11], v[120:121], v[10:11]
	v_cvt_pk_bf16_f32 v8, v8, v9
	v_cvt_pk_bf16_f32 v9, v10, v11
	global_store_dwordx2 v[0:1], v[8:9], off offset:96
	v_pk_mul_f32 v[8:9], v[134:135], v[80:81] op_sel_hi:[1,0]
	v_pk_mul_f32 v[10:11], v[128:129], v[80:81] op_sel_hi:[1,0]
	v_pk_fma_f32 v[8:9], v[24:25], v[8:9], v[72:73]
	v_pk_fma_f32 v[10:11], v[26:27], v[10:11], v[74:75]
	v_pk_mul_f32 v[8:9], v[70:71], v[8:9]
	v_pk_mul_f32 v[10:11], v[132:133], v[10:11]
	v_cvt_pk_bf16_f32 v8, v8, v9
	v_cvt_pk_bf16_f32 v9, v10, v11
	global_store_dwordx2 v[0:1], v[8:9], off offset:128
	v_pk_mul_f32 v[8:9], v[18:19], v[80:81] op_sel_hi:[1,0]
	v_pk_mul_f32 v[10:11], v[138:139], v[80:81] op_sel_hi:[1,0]
	v_pk_fma_f32 v[8:9], v[20:21], v[8:9], v[76:77]
	v_pk_fma_f32 v[10:11], v[10:11], v[22:23], v[78:79]
	v_pk_mul_f32 v[8:9], v[68:69], v[8:9]
	v_pk_mul_f32 v[10:11], v[142:143], v[10:11]
	v_cvt_pk_bf16_f32 v8, v8, v9
	v_cvt_pk_bf16_f32 v9, v10, v11
	global_store_dwordx2 v[0:1], v[8:9], off offset:160
	ds_read_b128 v[8:11], v83 offset:384
	ds_read_b128 v[12:15], v148 offset:384
	s_waitcnt vmcnt(7)
	v_lshlrev_b32_e32 v18, 16, v66
	v_and_b32_e32 v19, 0xffff0000, v66
	v_pk_mul_f32 v[16:17], v[16:17], v[80:81] op_sel_hi:[1,0]
	v_mul_f32_e32 v20, 0xbfb8aa3b, v18
	s_waitcnt lgkmcnt(0)
	v_pk_fma_f32 v[8:9], v[16:17], v[8:9], v[12:13]
	v_mul_f32_e32 v12, 0xbfb8aa3b, v19
	v_exp_f32_e32 v20, v20
	v_exp_f32_e32 v12, v12
	v_pk_mul_f32 v[6:7], v[6:7], v[80:81] op_sel_hi:[1,0]
	v_pk_mul_f32 v[4:5], v[4:5], v[80:81] op_sel_hi:[1,0]
	v_add_f32_e32 v20, 1.0, v20
	v_add_f32_e32 v12, 1.0, v12
	v_rcp_f32_e32 v20, v20
	v_rcp_f32_e32 v21, v12
	v_pk_fma_f32 v[6:7], v[6:7], v[10:11], v[14:15]
	s_waitcnt vmcnt(6)
	v_lshlrev_b32_e32 v14, 16, v64
	v_and_b32_e32 v15, 0xffff0000, v64
	v_pk_mul_f32 v[12:13], v[20:21], v[18:19]
	v_pk_mul_f32 v[2:3], v[2:3], v[80:81] op_sel_hi:[1,0]
	v_pk_mul_f32 v[8:9], v[12:13], v[8:9]
	v_lshlrev_b32_e32 v12, 16, v67
	v_cvt_pk_bf16_f32 v8, v8, v9
	v_mul_f32_e32 v9, 0xbfb8aa3b, v12
	v_exp_f32_e32 v9, v9
	v_and_b32_e32 v13, 0xffff0000, v67
	v_add_f32_e32 v9, 1.0, v9
	v_rcp_f32_e32 v16, v9
	v_mul_f32_e32 v9, 0xbfb8aa3b, v13
	v_exp_f32_e32 v9, v9
	s_nop 0
	v_add_f32_e32 v9, 1.0, v9
	v_rcp_f32_e32 v17, v9
	s_nop 0
	v_pk_mul_f32 v[10:11], v[16:17], v[12:13]
	s_nop 0
	v_pk_mul_f32 v[6:7], v[10:11], v[6:7]
	v_mul_f32_e32 v16, 0xbfb8aa3b, v14
	v_cvt_pk_bf16_f32 v9, v6, v7
	global_store_dwordx2 v[0:1], v[8:9], off offset:192
	ds_read_b128 v[6:9], v83 offset:448
	ds_read_b128 v[10:13], v148 offset:448
	v_exp_f32_e32 v16, v16
	s_waitcnt lgkmcnt(0)
	v_pk_fma_f32 v[4:5], v[4:5], v[6:7], v[10:11]
	v_mul_f32_e32 v6, 0xbfb8aa3b, v15
	v_exp_f32_e32 v6, v6
	v_add_f32_e32 v16, 1.0, v16
	v_rcp_f32_e32 v16, v16
	v_pk_fma_f32 v[2:3], v[2:3], v[8:9], v[12:13]
	v_add_f32_e32 v6, 1.0, v6
	v_rcp_f32_e32 v17, v6
	s_nop 0
	v_pk_mul_f32 v[6:7], v[16:17], v[14:15]
	s_nop 0
	v_pk_mul_f32 v[4:5], v[6:7], v[4:5]
	v_lshlrev_b32_e32 v6, 16, v65
	v_cvt_pk_bf16_f32 v4, v4, v5
	v_mul_f32_e32 v5, 0xbfb8aa3b, v6
	v_exp_f32_e32 v5, v5
	v_and_b32_e32 v7, 0xffff0000, v65
	v_add_f32_e32 v5, 1.0, v5
	v_rcp_f32_e32 v10, v5
	v_mul_f32_e32 v5, 0xbfb8aa3b, v7
	v_exp_f32_e32 v5, v5
	s_nop 0
	v_add_f32_e32 v5, 1.0, v5
	v_rcp_f32_e32 v11, v5
	s_nop 0
	v_pk_mul_f32 v[6:7], v[10:11], v[6:7]
	s_nop 0
	v_pk_mul_f32 v[2:3], v[6:7], v[2:3]
	s_nop 0
	v_cvt_pk_bf16_f32 v5, v2, v3
	global_store_dwordx2 v[0:1], v[4:5], off offset:224
	s_cbranch_scc1 .LBB0_189

; __device__ __forceinline__ void ret_out(const bf16_t* proj, const float* cosT, const float* sinT, const float* decay, const float* gn_g, const float* gn_b,
;                         const bf16_t* states, bf16_t* mix, unsigned char* lds, int tid, int bx) {
;     ...
;         const float lgf2 = -__expf(decay[h]) * 1.4426950408889634f, lgb2 = -__expf(decay[6 + h]) * 1.4426950408889634f;
; __global__ void __launch_bounds__(512, 2) mega(Params p) {
	.amdhsa_kernel _Z4mega6Params
		.amdhsa_group_segment_fixed_size 0
		.amdhsa_private_segment_fixed_size 0
		.amdhsa_kernarg_size 400
		.amdhsa_user_sgpr_count 2
		.amdhsa_user_sgpr_dispatch_ptr 0
		.amdhsa_user_sgpr_queue_ptr 0
		.amdhsa_user_sgpr_kernarg_segment_ptr 1
		.amdhsa_user_sgpr_dispatch_id 0
		.amdhsa_user_sgpr_kernarg_preload_length 0
		.amdhsa_user_sgpr_kernarg_preload_offset 0
		.amdhsa_user_sgpr_private_segment_size 0
		.amdhsa_uses_dynamic_stack 0
		.amdhsa_enable_private_segment 0
		.amdhsa_system_sgpr_workgroup_id_x 1
		.amdhsa_system_sgpr_workgroup_id_y 0
		.amdhsa_system_sgpr_workgroup_id_z 0
		.amdhsa_system_sgpr_workgroup_info 0
		.amdhsa_system_vgpr_workitem_id 2
		.amdhsa_next_free_vgpr 246
		.amdhsa_next_free_sgpr 102
		.amdhsa_accum_offset 248
		.amdhsa_reserve_vcc 1
		.amdhsa_float_round_mode_32 0
		.amdhsa_float_round_mode_16_64 0
		.amdhsa_float_denorm_mode_32 3
		.amdhsa_float_denorm_mode_16_64 3
		.amdhsa_dx10_clamp 1
		.amdhsa_ieee_mode 1
		.amdhsa_fp16_overflow 0
		.amdhsa_tg_split 0
		.amdhsa_exception_fp_ieee_invalid_op 0
		.amdhsa_exception_fp_denorm_src 0
		.amdhsa_exception_fp_ieee_div_zero 0
		.amdhsa_exception_fp_ieee_overflow 0
		.amdhsa_exception_fp_ieee_underflow 0
		.amdhsa_exception_fp_ieee_inexact 0
		.amdhsa_exception_int_div_zero 0
	.end_amdhsa_kernel

; __global__ void __launch_bounds__(512, 2) mega(Params p) {
amdhsa.kernels:
  - .agpr_count:     0
    .args:
      - .offset:         0
        .size:           144
        .value_kind:     by_value
      - .offset:         144
        .size:           4
        .value_kind:     hidden_block_count_x
      - .offset:         148
        .size:           4
        .value_kind:     hidden_block_count_y
      - .offset:         152
        .size:           4
        .value_kind:     hidden_block_count_z
      - .offset:         156
        .size:           2
        .value_kind:     hidden_group_size_x
      - .offset:         158
        .size:           2
        .value_kind:     hidden_group_size_y
      - .offset:         160
        .size:           2
        .value_kind:     hidden_group_size_z
      - .offset:         162
        .size:           2
        .value_kind:     hidden_remainder_x
      - .offset:         164
        .size:           2
        .value_kind:     hidden_remainder_y
      - .offset:         166
        .size:           2
        .value_kind:     hidden_remainder_z
      - .offset:         184
        .size:           8
        .value_kind:     hidden_global_offset_x
      - .offset:         192
        .size:           8
        .value_kind:     hidden_global_offset_y
      - .offset:         200
        .size:           8
        .value_kind:     hidden_global_offset_z
      - .offset:         208
        .size:           2
        .value_kind:     hidden_grid_dims
      - .offset:         232
        .size:           8
        .value_kind:     hidden_multigrid_sync_arg
      - .offset:         264
        .size:           4
        .value_kind:     hidden_dynamic_lds_size
    .group_segment_fixed_size: 0
    .kernarg_segment_align: 8
    .kernarg_segment_size: 400
    .language:       OpenCL C
    .language_version:
      - 2
      - 0
    .max_flat_workgroup_size: 512
    .name:           _Z4mega6Params
    .private_segment_fixed_size: 0
    .sgpr_count:     108
    .sgpr_spill_count: 105
    .symbol:         _Z4mega6Params.kd
    .uniform_work_group_size: 1
    .uses_dynamic_stack: false
    .vgpr_count:     246
    .vgpr_spill_count: 0
    .wavefront_size: 64
